# tmb + FFN-in B operand (w_i weights) also tile-major via P0
# speedup vs baseline: 1.0081x; 1.0006x over previous
; #define GAS __attribute__((address_space(1)))
;     if (ldk == 0) ldk = K;
;     const int nblk = (N + 63) / 64, kb = item / nblk, nb = item % nblk, k0 = 64 * kb, n0 = 64 * nb;
;     const bool ok = n0 + lane < N;
;     float tv[64];
;     { const GAS float* wp = (const GAS float*)(W + (size_t)k0 * N + n0 + (ok ? lane : 0));
; #pragma unroll
;       for (int i = 0; i < 64; ++i) tv[i] = wp[(size_t)i * N]; }
; __device__ __forceinline__ void p0_prologue(Frame& F, const Args& a) {
;     ...
;         const int itc_ = it++;
;         const int l = itc_ / PER_L; int r = itc_ % PER_L;
;         if (r < 2 * I_FI) { const int f = r / I_FI; p0_transpose_item64(a.in[5] + ((size_t)l * 2 + f) * D * 2 * FF, D, 2 * FF, (bf16*)(ws + WS_WFI + ((size_t)l * 2 + f) * SZ_WFI1), MapFfnIn(), scu, r % I_FI, F.lane); continue; } r -= 2 * I_FI;
.LBB0_111:
	s_andn2_b64 vcc, exec, s[4:5]
	s_cbranch_vccnz .LBB0_28
	s_mul_i32 s1, s31, 0xba3
	s_lshr_b32 s4, s1, 31
	s_ashr_i32 s1, s1, 24
	s_add_i32 s1, s1, s4
	s_lshl_b32 s0, s0, 1
	s_add_i32 s0, s0, s1
	s_mul_i32 s5, s0, 0x5800000
	s_mul_hi_i32 s4, s0, 0x5800000
	s_add_u32 s28, s16, s5
	s_addc_u32 s29, s17, s4
	s_mul_hi_i32 s4, s0, 0x2c00000
	s_mul_i32 s0, s0, 0x2c00000
	s_add_u32 s26, s45, s0
	s_mulk_i32 s1, 0x1600
	s_addc_u32 s27, s46, s4
	s_sub_i32 s0, s31, s1
	s_sext_i32_i16 s1, s0
	s_mulk_i32 s1, 0xba3
	s_lshr_b32 s4, s1, 31
	s_ashr_i32 s1, s1, 19
	s_add_i32 s1, s1, s4
	s_mul_i32 s4, s1, 0xb0
	s_sub_i32 s0, s0, s4
	s_sext_i32_i16 s0, s0
	s_lshl_b32 s4, s1, 6
	s_lshl_b32 s0, s0, 6
	s_ashr_i32 s5, s4, 31
	s_mul_i32 s1, s1, 0x2c0000
	s_mul_hi_i32 s31, s4, 0xb000
	s_add_u32 s34, s28, s1
	v_or_b32_e32 v2, s0, v10
	s_addc_u32 s31, s29, s31
	s_ashr_i32 s1, s0, 31
	v_cmp_gt_i32_e32 vcc, s55, v2
	s_lshl_b64 s[28:29], s[0:1], 2
	s_add_u32 s28, s34, s28
	v_cndmask_b32_e32 v2, 0, v10, vcc
	s_addc_u32 s29, s31, s29
	v_lshlrev_b32_e32 v4, 2, v2
	v_mov_b32_e32 v5, v13
	v_lshl_add_u64 v[2:3], s[28:29], 0, v[4:5]
	s_mov_b32 s1, 0xb000
	v_add_co_u32_e32 v6, vcc, s1, v2
	s_mov_b32 s1, 0x37000
	s_nop 0
	v_addc_co_u32_e32 v7, vcc, 0, v3, vcc
	global_load_dword v5, v[6:7], off
	v_add_co_u32_e32 v6, vcc, s57, v2
	global_load_dword v4, v4, s[28:29]
	s_nop 0
	v_addc_co_u32_e32 v7, vcc, 0, v3, vcc
	v_add_co_u32_e32 v8, vcc, s49, v2
	global_load_dword v6, v[6:7], off
	s_nop 0
	v_addc_co_u32_e32 v9, vcc, 0, v3, vcc
	global_load_dword v7, v[8:9], off
	v_add_co_u32_e32 v8, vcc, s68, v2
	s_lshl_b64 s[4:5], s[4:5], 9
	s_nop 0
	v_addc_co_u32_e32 v9, vcc, 0, v3, vcc
	v_add_co_u32_e32 v16, vcc, s1, v2
	global_load_dword v8, v[8:9], off
	s_nop 0
	v_addc_co_u32_e32 v17, vcc, 0, v3, vcc
	global_load_dword v9, v[16:17], off
	v_add_co_u32_e32 v16, vcc, s79, v2
	s_mov_b32 s1, 0x4d000
	s_nop 0
	v_addc_co_u32_e32 v17, vcc, 0, v3, vcc
	global_load_dword v15, v[16:17], off
	v_add_co_u32_e32 v16, vcc, s1, v2
	s_mov_b32 s1, 0x63000
	s_nop 0
	v_addc_co_u32_e32 v17, vcc, 0, v3, vcc
	v_add_co_u32_e32 v38, vcc, s90, v2
	global_load_dword v16, v[16:17], off
	s_nop 0
	v_addc_co_u32_e32 v39, vcc, 0, v3, vcc
	global_load_dword v17, v[38:39], off
	v_add_co_u32_e32 v38, vcc, s1, v2
	s_mov_b32 s1, 0x79000
	s_nop 0
	v_addc_co_u32_e32 v39, vcc, 0, v3, vcc
	v_add_co_u32_e32 v40, vcc, s38, v2
	global_load_dword v38, v[38:39], off
	s_nop 0
	v_addc_co_u32_e32 v41, vcc, 0, v3, vcc
	global_load_dword v39, v[40:41], off
	v_add_co_u32_e32 v40, vcc, s1, v2
	s_mov_b32 s1, 0x84000
	s_nop 0
	v_addc_co_u32_e32 v41, vcc, 0, v3, vcc
	v_add_co_u32_e32 v42, vcc, s1, v2
	s_mov_b32 s1, 0x8f000
	s_nop 0
	v_addc_co_u32_e32 v43, vcc, 0, v3, vcc
	global_load_dword v40, v[40:41], off
	s_add_u32 s4, s26, s4
	global_load_dword v41, v[42:43], off
	v_add_co_u32_e32 v42, vcc, s1, v2
	s_mov_b32 s1, 0x9a000
	s_nop 0
	v_addc_co_u32_e32 v43, vcc, 0, v3, vcc
	v_add_co_u32_e32 v44, vcc, s1, v2
	s_mov_b32 s1, 0xa5000
	s_nop 0
	v_addc_co_u32_e32 v45, vcc, 0, v3, vcc
	global_load_dword v42, v[42:43], off
	s_addc_u32 s5, s27, s5
	global_load_dword v43, v[44:45], off
	v_add_co_u32_e32 v44, vcc, s1, v2
	s_mov_b32 s1, 0xb0000
	s_nop 0
	v_addc_co_u32_e32 v45, vcc, 0, v3, vcc
	v_add_co_u32_e32 v46, vcc, s1, v2
	s_mov_b32 s1, 0xbb000
	s_nop 0
	v_addc_co_u32_e32 v47, vcc, 0, v3, vcc
	global_load_dword v44, v[44:45], off
	s_nop 0
	global_load_dword v45, v[46:47], off
	v_add_co_u32_e32 v46, vcc, s1, v2
	s_mov_b32 s1, 0xc6000
	s_nop 0
	v_addc_co_u32_e32 v47, vcc, 0, v3, vcc
	v_add_co_u32_e32 v48, vcc, s1, v2
	s_mov_b32 s1, 0xd1000
	s_nop 0
	v_addc_co_u32_e32 v49, vcc, 0, v3, vcc
	global_load_dword v46, v[46:47], off
	s_nop 0
	global_load_dword v47, v[48:49], off
	v_add_co_u32_e32 v48, vcc, s1, v2
	s_mov_b32 s1, 0xdc000
	s_nop 0
	v_addc_co_u32_e32 v49, vcc, 0, v3, vcc
	v_add_co_u32_e32 v50, vcc, s1, v2
	s_mov_b32 s1, 0xe7000
	s_nop 0
	v_addc_co_u32_e32 v51, vcc, 0, v3, vcc
	global_load_dword v48, v[48:49], off
	s_nop 0
	global_load_dword v49, v[50:51], off
	v_add_co_u32_e32 v50, vcc, s1, v2
	s_mov_b32 s1, 0xf2000
	s_nop 0
	v_addc_co_u32_e32 v51, vcc, 0, v3, vcc
	v_add_co_u32_e32 v52, vcc, s1, v2
	s_mov_b32 s1, 0xfd000
	s_nop 0
	v_addc_co_u32_e32 v53, vcc, 0, v3, vcc
	global_load_dword v50, v[50:51], off
	s_nop 0
	global_load_dword v51, v[52:53], off
	v_add_co_u32_e32 v52, vcc, s1, v2
	s_mov_b32 s1, 0x108000
	s_nop 0
	v_addc_co_u32_e32 v53, vcc, 0, v3, vcc
	v_add_co_u32_e32 v54, vcc, s1, v2
	global_load_dword v52, v[52:53], off
	s_nop 0
	v_addc_co_u32_e32 v55, vcc, 0, v3, vcc
	global_load_dword v53, v[54:55], off
	v_add_co_u32_e32 v54, vcc, s51, v2
	s_mov_b32 s1, 0x11e000
	s_nop 0
	v_addc_co_u32_e32 v55, vcc, 0, v3, vcc
	global_load_dword v56, v[54:55], off
	v_add_co_u32_e32 v54, vcc, s1, v2
	s_mov_b32 s1, 0x129000
	s_nop 0
	v_addc_co_u32_e32 v55, vcc, 0, v3, vcc
	global_load_dword v57, v[54:55], off
	v_add_co_u32_e32 v54, vcc, s1, v2
	s_mov_b32 s1, 0x13f000
	s_nop 0
	v_addc_co_u32_e32 v55, vcc, 0, v3, vcc
	global_load_dword v58, v[54:55], off
	v_add_co_u32_e32 v54, vcc, s52, v2
	s_nop 1
	v_addc_co_u32_e32 v55, vcc, 0, v3, vcc
	global_load_dword v59, v[54:55], off
	v_add_co_u32_e32 v54, vcc, s1, v2
	s_mov_b32 s1, 0x14a000
	s_nop 0
	v_addc_co_u32_e32 v55, vcc, 0, v3, vcc
	global_load_dword v60, v[54:55], off
	v_add_co_u32_e32 v54, vcc, s1, v2
	s_mov_b32 s1, 0x155000
	s_nop 0
	v_addc_co_u32_e32 v55, vcc, 0, v3, vcc
	global_load_dword v61, v[54:55], off
	v_add_co_u32_e32 v54, vcc, s1, v2
	s_mov_b32 s1, 0x160000
	s_nop 0
	v_addc_co_u32_e32 v55, vcc, 0, v3, vcc
	global_load_dword v62, v[54:55], off
	v_add_co_u32_e32 v54, vcc, s1, v2
; __device__ __forceinline__ unsigned cvt_pk_bf16(float lo, float hi) { const pk_f2_t v = {lo, hi}; return __builtin_bit_cast(unsigned, __builtin_convertvector(v, pk_bf2_t)); }
;     ...
;       for (int i = 0; i < 64; ++i) tv[i] = wp[(size_t)i * N]; }
; #pragma unroll
;     for (int j = 0; j < 32; ++j) scr[j * 65 + lane] = pg8::cvt_pk_bf16(tv[2 * j], tv[2 * j + 1]);
	s_mov_b32 s1, 0x16b000
	s_nop 0
	v_addc_co_u32_e32 v55, vcc, 0, v3, vcc
	global_load_dword v63, v[54:55], off
	v_add_co_u32_e32 v54, vcc, s1, v2
	s_mov_b32 s1, 0x176000
	s_nop 0
	v_addc_co_u32_e32 v55, vcc, 0, v3, vcc
	global_load_dword v64, v[54:55], off
	v_add_co_u32_e32 v54, vcc, s1, v2
	s_mov_b32 s1, 0x181000
	s_nop 0
	v_addc_co_u32_e32 v55, vcc, 0, v3, vcc
	global_load_dword v65, v[54:55], off
	v_add_co_u32_e32 v54, vcc, s1, v2
	s_mov_b32 s1, 0x18c000
	s_nop 0
	v_addc_co_u32_e32 v55, vcc, 0, v3, vcc
	global_load_dword v66, v[54:55], off
	v_add_co_u32_e32 v54, vcc, s1, v2
	s_mov_b32 s1, 0x197000
	s_nop 0
	v_addc_co_u32_e32 v55, vcc, 0, v3, vcc
	global_load_dword v67, v[54:55], off
	v_add_co_u32_e32 v54, vcc, s1, v2
	s_mov_b32 s1, 0x1a2000
	s_nop 0
	v_addc_co_u32_e32 v55, vcc, 0, v3, vcc
	global_load_dword v68, v[54:55], off
	v_add_co_u32_e32 v54, vcc, s1, v2
	s_mov_b32 s1, 0x1ad000
	s_nop 0
	v_addc_co_u32_e32 v55, vcc, 0, v3, vcc
	global_load_dword v69, v[54:55], off
	v_add_co_u32_e32 v54, vcc, s1, v2
	s_mov_b32 s1, 0x1b8000
	s_nop 0
	v_addc_co_u32_e32 v55, vcc, 0, v3, vcc
	global_load_dword v70, v[54:55], off
	v_add_co_u32_e32 v54, vcc, s1, v2
	s_mov_b32 s1, 0x1c3000
	s_nop 0
	v_addc_co_u32_e32 v55, vcc, 0, v3, vcc
	global_load_dword v71, v[54:55], off
	v_add_co_u32_e32 v54, vcc, s1, v2
	s_mov_b32 s1, 0x1ce000
	s_nop 0
	v_addc_co_u32_e32 v55, vcc, 0, v3, vcc
	global_load_dword v72, v[54:55], off
	v_add_co_u32_e32 v54, vcc, s1, v2
	s_mov_b32 s1, 0x1d9000
	s_nop 0
	v_addc_co_u32_e32 v55, vcc, 0, v3, vcc
	global_load_dword v73, v[54:55], off
	v_add_co_u32_e32 v54, vcc, s1, v2
	s_mov_b32 s1, 0x1e4000
	s_nop 0
	v_addc_co_u32_e32 v55, vcc, 0, v3, vcc
	global_load_dword v74, v[54:55], off
	v_add_co_u32_e32 v54, vcc, s1, v2
	s_mov_b32 s1, 0x1ef000
	s_nop 0
	v_addc_co_u32_e32 v55, vcc, 0, v3, vcc
	global_load_dword v75, v[54:55], off
	v_add_co_u32_e32 v54, vcc, s1, v2
	s_mov_b32 s1, 0x1fa000
	s_nop 0
	v_addc_co_u32_e32 v55, vcc, 0, v3, vcc
	global_load_dword v76, v[54:55], off
	v_add_co_u32_e32 v54, vcc, s1, v2
	s_mov_b32 s1, 0x210000
	s_nop 0
	v_addc_co_u32_e32 v55, vcc, 0, v3, vcc
	global_load_dword v77, v[54:55], off
	v_add_co_u32_e32 v54, vcc, s53, v2
	s_nop 1
	v_addc_co_u32_e32 v55, vcc, 0, v3, vcc
	global_load_dword v78, v[54:55], off
	v_add_co_u32_e32 v54, vcc, s1, v2
	s_mov_b32 s1, 0x21b000
	s_nop 0
	v_addc_co_u32_e32 v55, vcc, 0, v3, vcc
	global_load_dword v79, v[54:55], off
	v_add_co_u32_e32 v54, vcc, s1, v2
	s_mov_b32 s1, 0x226000
	s_nop 0
	v_addc_co_u32_e32 v55, vcc, 0, v3, vcc
	global_load_dword v80, v[54:55], off
	v_add_co_u32_e32 v54, vcc, s1, v2
	s_mov_b32 s1, 0x231000
	s_nop 0
	v_addc_co_u32_e32 v55, vcc, 0, v3, vcc
	global_load_dword v81, v[54:55], off
	v_add_co_u32_e32 v54, vcc, s1, v2
	s_mov_b32 s1, 0x23c000
	s_nop 0
	v_addc_co_u32_e32 v55, vcc, 0, v3, vcc
	global_load_dword v83, v[54:55], off
	v_add_co_u32_e32 v54, vcc, s1, v2
	s_mov_b32 s1, 0x247000
	s_nop 0
	v_addc_co_u32_e32 v55, vcc, 0, v3, vcc
	global_load_dword v84, v[54:55], off
	v_add_co_u32_e32 v54, vcc, s1, v2
	s_mov_b32 s1, 0x252000
	s_nop 0
	v_addc_co_u32_e32 v55, vcc, 0, v3, vcc
	global_load_dword v85, v[54:55], off
	v_add_co_u32_e32 v54, vcc, s1, v2
	s_mov_b32 s1, 0x25d000
	s_nop 0
	v_addc_co_u32_e32 v55, vcc, 0, v3, vcc
	global_load_dword v86, v[54:55], off
	v_add_co_u32_e32 v54, vcc, s1, v2
	s_mov_b32 s1, 0x268000
	s_nop 0
	v_addc_co_u32_e32 v55, vcc, 0, v3, vcc
	global_load_dword v87, v[54:55], off
	v_add_co_u32_e32 v54, vcc, s1, v2
	s_mov_b32 s1, 0x273000
	s_nop 0
	v_addc_co_u32_e32 v55, vcc, 0, v3, vcc
	global_load_dword v88, v[54:55], off
	v_add_co_u32_e32 v54, vcc, s1, v2
	s_mov_b32 s1, 0x27e000
	s_nop 0
	v_addc_co_u32_e32 v55, vcc, 0, v3, vcc
	global_load_dword v89, v[54:55], off
	v_add_co_u32_e32 v54, vcc, s1, v2
	s_mov_b32 s1, 0x289000
	s_nop 0
	v_addc_co_u32_e32 v55, vcc, 0, v3, vcc
	global_load_dword v90, v[54:55], off
	v_add_co_u32_e32 v54, vcc, s1, v2
	s_mov_b32 s1, 0x294000
	s_nop 0
	v_addc_co_u32_e32 v55, vcc, 0, v3, vcc
	global_load_dword v91, v[54:55], off
	v_add_co_u32_e32 v54, vcc, s1, v2
	s_mov_b32 s1, 0x29f000
	s_nop 0
	v_addc_co_u32_e32 v55, vcc, 0, v3, vcc
	global_load_dword v92, v[54:55], off
	v_add_co_u32_e32 v54, vcc, s1, v2
	s_mov_b32 s1, 0x2aa000
	s_nop 0
	v_addc_co_u32_e32 v55, vcc, 0, v3, vcc
	global_load_dword v93, v[54:55], off
	v_add_co_u32_e32 v54, vcc, s1, v2
	s_mov_b32 s1, 0x2b5000
	s_nop 0
	v_addc_co_u32_e32 v55, vcc, 0, v3, vcc
	v_add_co_u32_e32 v2, vcc, s1, v2
	global_load_dword v54, v[54:55], off
	s_nop 0
	v_addc_co_u32_e32 v3, vcc, 0, v3, vcc
	global_load_dword v2, v[2:3], off
	s_waitcnt vmcnt(62)
	v_cvt_pk_bf16_f32 v3, v4, v5
	s_waitcnt vmcnt(60)
	v_cvt_pk_bf16_f32 v4, v6, v7
	ds_write2_b32 v22, v3, v4 offset1:65
	s_waitcnt vmcnt(58)
	v_cvt_pk_bf16_f32 v3, v8, v9
	s_waitcnt vmcnt(56)
	v_cvt_pk_bf16_f32 v4, v15, v16
	ds_write2_b32 v22, v3, v4 offset0:130 offset1:195
	s_waitcnt vmcnt(54)
	v_cvt_pk_bf16_f32 v3, v17, v38
	s_waitcnt vmcnt(52)
	v_cvt_pk_bf16_f32 v4, v39, v40
	ds_write2_b32 v28, v3, v4 offset0:4 offset1:69
	s_waitcnt vmcnt(50)
	v_cvt_pk_bf16_f32 v3, v41, v42
	s_waitcnt vmcnt(48)
	v_cvt_pk_bf16_f32 v4, v43, v44
	ds_write2_b32 v28, v3, v4 offset0:134 offset1:199
	s_waitcnt vmcnt(46)
	v_cvt_pk_bf16_f32 v3, v45, v46
	s_waitcnt vmcnt(44)
	v_cvt_pk_bf16_f32 v4, v47, v48
	ds_write2_b32 v29, v3, v4 offset0:8 offset1:73
	s_waitcnt vmcnt(42)
	v_cvt_pk_bf16_f32 v3, v49, v50
	s_waitcnt vmcnt(40)
	v_cvt_pk_bf16_f32 v4, v51, v52
	ds_write2_b32 v29, v3, v4 offset0:138 offset1:203
	s_waitcnt vmcnt(38)
	v_cvt_pk_bf16_f32 v3, v53, v56
	s_waitcnt vmcnt(36)
	v_cvt_pk_bf16_f32 v4, v57, v58
	ds_write2_b32 v30, v3, v4 offset0:12 offset1:77
	s_waitcnt vmcnt(34)
; __device__ __forceinline__ unsigned cvt_pk_bf16(float lo, float hi) { const pk_f2_t v = {lo, hi}; return __builtin_bit_cast(unsigned, __builtin_convertvector(v, pk_bf2_t)); }
; #define GAS __attribute__((address_space(1)))
; #define LAS __attribute__((address_space(3)))
; #define LDS_WAIT() asm volatile("s_waitcnt lgkmcnt(0)" ::: "memory")
;     ...
;     for (int j = 0; j < 32; ++j) scr[j * 65 + lane] = pg8::cvt_pk_bf16(tv[2 * j], tv[2 * j + 1]);
;     LDS_WAIT(); asm volatile("" ::: "memory");
;     const int c = lane & 7;
; #pragma unroll
;     for (int jj = 0; jj < 8; ++jj) { const int n = (lane >> 3) + 8 * jj; const LAS unsigned* q = scr + (4 * c) * 65 + n;
;         v4u o; o.x = q[0]; o.y = q[65]; o.z = q[130]; o.w = q[195];
;         if (n0 + n < N) *(GAS v4u*)(WT + (size_t)mp(n0 + n) * ldk + koff + k0 + 8 * c) = o; }
	v_cvt_pk_bf16_f32 v3, v59, v60
	s_waitcnt vmcnt(32)
	v_cvt_pk_bf16_f32 v4, v61, v62
	ds_write2_b32 v30, v3, v4 offset0:142 offset1:207
	s_waitcnt vmcnt(30)
	v_cvt_pk_bf16_f32 v3, v63, v64
	s_waitcnt vmcnt(28)
	v_cvt_pk_bf16_f32 v4, v65, v66
	ds_write2_b32 v31, v3, v4 offset0:16 offset1:81
	s_waitcnt vmcnt(26)
	v_cvt_pk_bf16_f32 v3, v67, v68
	s_waitcnt vmcnt(24)
	v_cvt_pk_bf16_f32 v4, v69, v70
	ds_write2_b32 v31, v3, v4 offset0:146 offset1:211
	s_waitcnt vmcnt(22)
	v_cvt_pk_bf16_f32 v3, v71, v72
	s_waitcnt vmcnt(20)
	v_cvt_pk_bf16_f32 v4, v73, v74
	ds_write2_b32 v32, v3, v4 offset0:20 offset1:85
	s_waitcnt vmcnt(18)
	v_cvt_pk_bf16_f32 v3, v75, v76
	s_waitcnt vmcnt(16)
	v_cvt_pk_bf16_f32 v4, v77, v78
	ds_write2_b32 v32, v3, v4 offset0:150 offset1:215
	s_waitcnt vmcnt(14)
	v_cvt_pk_bf16_f32 v3, v79, v80
	s_waitcnt vmcnt(12)
	v_cvt_pk_bf16_f32 v4, v81, v83
	ds_write2_b32 v33, v3, v4 offset0:24 offset1:89
	s_waitcnt vmcnt(10)
	v_cvt_pk_bf16_f32 v3, v84, v85
	s_waitcnt vmcnt(8)
	v_cvt_pk_bf16_f32 v4, v86, v87
	ds_write2_b32 v33, v3, v4 offset0:154 offset1:219
	s_waitcnt vmcnt(6)
	v_cvt_pk_bf16_f32 v3, v88, v89
	s_waitcnt vmcnt(4)
	v_cvt_pk_bf16_f32 v4, v90, v91
	ds_write2_b32 v34, v3, v4 offset0:28 offset1:93
	v_or_b32_e32 v4, s0, v11
	v_cmp_gt_i32_e32 vcc, s55, v4
	s_waitcnt vmcnt(2)
	v_cvt_pk_bf16_f32 v3, v92, v93
	s_waitcnt vmcnt(0)
	v_cvt_pk_bf16_f32 v2, v54, v2
	ds_write2_b32 v34, v3, v2 offset0:158 offset1:223
	s_waitcnt lgkmcnt(0)
	v_lshl_add_u64 v[2:3], s[4:5], 0, v[12:13]
	s_and_saveexec_b64 s[4:5], vcc
	s_cbranch_execz .LBB0_114
	v_add_u32_e32 v5, 0xffffea00, v4
	v_cmp_lt_i32_e32 vcc, s56, v4
	ds_read2_b32 v[6:7], v23 offset1:65
	ds_read2_b32 v[8:9], v23 offset0:130 offset1:195
	v_cndmask_b32_e32 v4, v4, v5, vcc
	v_lshlrev_b32_e32 v5, 1, v4
	v_and_b32_e32 v5, 0xffffff00, v5
	v_cndmask_b32_e32 v15, 0, v37, vcc
	v_and_b32_e32 v4, 0x47, v4
	v_or3_b32 v4, v4, v15, v5
	v_ashrrev_i32_e32 v5, 31, v4
	v_and_b32_e32 v15, 0xff, v4
	v_lshrrev_b32_e32 v4, 8, v4
	v_lshlrev_b32_e32 v4, 20, v4
	v_lshl_or_b32 v4, v15, 7, v4
	v_mov_b32_e32 v5, 0
	v_lshl_add_u64 v[4:5], v[2:3], 0, v[4:5]
	s_waitcnt lgkmcnt(0)
	global_store_dwordx4 v[4:5], v[6:9], off
.LBB0_114:
	s_or_b64 exec, exec, s[4:5]
	v_or_b32_e32 v4, s0, v18
	v_cmp_gt_i32_e32 vcc, s55, v4
	s_and_saveexec_b64 s[4:5], vcc
	s_cbranch_execz .LBB0_116
	v_add_u32_e32 v5, 0xffffea00, v4
	v_cmp_lt_i32_e32 vcc, s56, v4
	ds_read2_b32 v[6:7], v23 offset0:8 offset1:73
	ds_read2_b32 v[8:9], v23 offset0:138 offset1:203
	v_cndmask_b32_e32 v4, v4, v5, vcc
	v_lshlrev_b32_e32 v5, 1, v4
	v_and_b32_e32 v5, 0xffffff00, v5
	v_cndmask_b32_e32 v15, 0, v37, vcc
	v_and_b32_e32 v4, 0x7f, v4
	v_or3_b32 v4, v4, v15, v5
	v_ashrrev_i32_e32 v5, 31, v4
	v_and_b32_e32 v15, 0xff, v4
	v_lshrrev_b32_e32 v4, 8, v4
	v_lshlrev_b32_e32 v4, 20, v4
	v_lshl_or_b32 v4, v15, 7, v4
	v_mov_b32_e32 v5, 0
	v_lshl_add_u64 v[4:5], v[2:3], 0, v[4:5]
	s_waitcnt lgkmcnt(0)
	global_store_dwordx4 v[4:5], v[6:9], off
.LBB0_116:
	s_or_b64 exec, exec, s[4:5]
	v_or_b32_e32 v4, s0, v19
	v_cmp_gt_i32_e32 vcc, s55, v4
	s_and_saveexec_b64 s[4:5], vcc
	s_cbranch_execz .LBB0_118
	v_add_u32_e32 v5, 0xffffea00, v4
	v_cmp_lt_i32_e32 vcc, s56, v4
	ds_read2_b32 v[6:7], v23 offset0:16 offset1:81
	ds_read2_b32 v[8:9], v23 offset0:146 offset1:211
	v_cndmask_b32_e32 v4, v4, v5, vcc
	v_lshlrev_b32_e32 v5, 1, v4
	v_and_b32_e32 v5, 0xffffff00, v5
	v_cndmask_b32_e32 v15, 0, v37, vcc
	v_and_b32_e32 v4, 0x7f, v4
	v_or3_b32 v4, v4, v15, v5
	v_ashrrev_i32_e32 v5, 31, v4
	v_and_b32_e32 v15, 0xff, v4
	v_lshrrev_b32_e32 v4, 8, v4
	v_lshlrev_b32_e32 v4, 20, v4
	v_lshl_or_b32 v4, v15, 7, v4
	v_mov_b32_e32 v5, 0
	v_lshl_add_u64 v[4:5], v[2:3], 0, v[4:5]
	s_waitcnt lgkmcnt(0)
	global_store_dwordx4 v[4:5], v[6:9], off
; #define GAS __attribute__((address_space(1)))
; #define LAS __attribute__((address_space(3)))
;     ...
;     for (int jj = 0; jj < 8; ++jj) { const int n = (lane >> 3) + 8 * jj; const LAS unsigned* q = scr + (4 * c) * 65 + n;
;         v4u o; o.x = q[0]; o.y = q[65]; o.z = q[130]; o.w = q[195];
;         if (n0 + n < N) *(GAS v4u*)(WT + (size_t)mp(n0 + n) * ldk + koff + k0 + 8 * c) = o; }
.LBB0_118:
	s_or_b64 exec, exec, s[4:5]
	v_or_b32_e32 v4, s0, v20
	v_cmp_gt_i32_e32 vcc, s55, v4
	s_and_saveexec_b64 s[4:5], vcc
	s_cbranch_execz .LBB0_120
	v_add_u32_e32 v5, 0xffffea00, v4
	v_cmp_lt_i32_e32 vcc, s56, v4
	ds_read2_b32 v[6:7], v23 offset0:24 offset1:89
	ds_read2_b32 v[8:9], v23 offset0:154 offset1:219
	v_cndmask_b32_e32 v4, v4, v5, vcc
	v_lshlrev_b32_e32 v5, 1, v4
	v_and_b32_e32 v5, 0xffffff00, v5
	v_cndmask_b32_e32 v15, 0, v37, vcc
	v_and_b32_e32 v4, 0x7f, v4
	v_or3_b32 v4, v4, v15, v5
	v_ashrrev_i32_e32 v5, 31, v4
	v_and_b32_e32 v15, 0xff, v4
	v_lshrrev_b32_e32 v4, 8, v4
	v_lshlrev_b32_e32 v4, 20, v4
	v_lshl_or_b32 v4, v15, 7, v4
	v_mov_b32_e32 v5, 0
	v_lshl_add_u64 v[4:5], v[2:3], 0, v[4:5]
	s_waitcnt lgkmcnt(0)
	global_store_dwordx4 v[4:5], v[6:9], off
.LBB0_120:
	s_or_b64 exec, exec, s[4:5]
	v_or_b32_e32 v4, s0, v24
	v_cmp_gt_i32_e32 vcc, s55, v4
	s_and_saveexec_b64 s[4:5], vcc
	s_cbranch_execz .LBB0_122
	v_add_u32_e32 v5, 0xffffea00, v4
	v_cmp_lt_i32_e32 vcc, s56, v4
	ds_read2_b32 v[6:7], v23 offset0:32 offset1:97
	ds_read2_b32 v[8:9], v23 offset0:162 offset1:227
	v_cndmask_b32_e32 v4, v4, v5, vcc
	v_lshlrev_b32_e32 v5, 1, v4
	v_and_b32_e32 v5, 0xffffff00, v5
	v_cndmask_b32_e32 v15, 0, v37, vcc
	v_and_b32_e32 v4, 0x7f, v4
	v_or3_b32 v4, v4, v15, v5
	v_ashrrev_i32_e32 v5, 31, v4
	v_and_b32_e32 v15, 0xff, v4
	v_lshrrev_b32_e32 v4, 8, v4
	v_lshlrev_b32_e32 v4, 20, v4
	v_lshl_or_b32 v4, v15, 7, v4
	v_mov_b32_e32 v5, 0
	v_lshl_add_u64 v[4:5], v[2:3], 0, v[4:5]
	s_waitcnt lgkmcnt(0)
	global_store_dwordx4 v[4:5], v[6:9], off
.LBB0_122:
	s_or_b64 exec, exec, s[4:5]
	v_or_b32_e32 v4, s0, v25
	v_cmp_gt_i32_e32 vcc, s55, v4
	s_and_saveexec_b64 s[4:5], vcc
	s_cbranch_execz .LBB0_124
	v_add_u32_e32 v5, 0xffffea00, v4
	v_cmp_lt_i32_e32 vcc, s56, v4
	ds_read2_b32 v[6:7], v23 offset0:40 offset1:105
	ds_read2_b32 v[8:9], v23 offset0:170 offset1:235
	v_cndmask_b32_e32 v4, v4, v5, vcc
	v_lshlrev_b32_e32 v5, 1, v4
	v_and_b32_e32 v5, 0xffffff00, v5
	v_cndmask_b32_e32 v15, 0, v37, vcc
	v_and_b32_e32 v4, 0x7f, v4
	v_or3_b32 v4, v4, v15, v5
	v_ashrrev_i32_e32 v5, 31, v4
	v_and_b32_e32 v15, 0xff, v4
	v_lshrrev_b32_e32 v4, 8, v4
	v_lshlrev_b32_e32 v4, 20, v4
	v_lshl_or_b32 v4, v15, 7, v4
	v_mov_b32_e32 v5, 0
	v_lshl_add_u64 v[4:5], v[2:3], 0, v[4:5]
	s_waitcnt lgkmcnt(0)
	global_store_dwordx4 v[4:5], v[6:9], off
.LBB0_124:
	s_or_b64 exec, exec, s[4:5]
	v_or_b32_e32 v4, s0, v26
	v_cmp_gt_i32_e32 vcc, s55, v4
	s_and_saveexec_b64 s[4:5], vcc
	s_cbranch_execz .LBB0_126
	v_add_u32_e32 v5, 0xffffea00, v4
	v_cmp_lt_i32_e32 vcc, s56, v4
	ds_read2_b32 v[6:7], v23 offset0:48 offset1:113
	ds_read2_b32 v[8:9], v23 offset0:178 offset1:243
	v_cndmask_b32_e32 v4, v4, v5, vcc
	v_lshlrev_b32_e32 v5, 1, v4
	v_and_b32_e32 v5, 0xffffff00, v5
	v_cndmask_b32_e32 v15, 0, v37, vcc
	v_and_b32_e32 v4, 0x7f, v4
	v_or3_b32 v4, v4, v15, v5
	v_ashrrev_i32_e32 v5, 31, v4
	v_and_b32_e32 v15, 0xff, v4
	v_lshrrev_b32_e32 v4, 8, v4
	v_lshlrev_b32_e32 v4, 20, v4
	v_lshl_or_b32 v4, v15, 7, v4
	v_mov_b32_e32 v5, 0
	v_lshl_add_u64 v[4:5], v[2:3], 0, v[4:5]
	s_waitcnt lgkmcnt(0)
	global_store_dwordx4 v[4:5], v[6:9], off
.LBB0_126:
	s_or_b64 exec, exec, s[4:5]
	v_or_b32_e32 v4, s0, v27
	v_cmp_gt_i32_e32 vcc, s55, v4
	s_and_saveexec_b64 s[0:1], vcc
	s_cbranch_execz .LBB0_27
	v_add_u32_e32 v5, 0xffffea00, v4
	v_cmp_lt_i32_e32 vcc, s56, v4
	ds_read2_b32 v[6:7], v23 offset0:56 offset1:121
	ds_read2_b32 v[8:9], v23 offset0:186 offset1:251
	v_cndmask_b32_e32 v4, v4, v5, vcc
	v_lshlrev_b32_e32 v5, 1, v4
	v_and_b32_e32 v5, 0xffffff00, v5
	v_cndmask_b32_e32 v15, 0, v37, vcc
	v_and_b32_e32 v4, 0x7f, v4
	v_or3_b32 v4, v4, v15, v5
	v_ashrrev_i32_e32 v5, 31, v4
	v_and_b32_e32 v15, 0xff, v4
	v_lshrrev_b32_e32 v4, 8, v4
	v_lshlrev_b32_e32 v4, 20, v4
	v_lshl_or_b32 v4, v15, 7, v4
	v_mov_b32_e32 v5, 0
	v_lshl_add_u64 v[2:3], v[2:3], 0, v[4:5]
	s_waitcnt lgkmcnt(0)
	global_store_dwordx4 v[2:3], v[6:9], off
	s_branch .LBB0_27

; template <class Epi, class Sched, bool ALIGN_EPI = false, bool SP2 = false>
; __device__ __forceinline__ void gemm_phase(PG8_LAS unsigned char* lds, const Gemm g, const Sched& S, const Epi& E, int wave_s) {
;     int tid_ = (wave_s << 6) | fresh_lane(); asm volatile("" : "+v"(tid_));
;     const int tid = tid_, wid = __builtin_amdgcn_readfirstlane(tid >> 6), lane = tid & 63, wr = wid >> 2, wc = wid & 3, fr = lane & 15, fq = lane >> 4;
;     const int K = g.K, nt = K / BK;
;     unsigned voffA[2], voffB[2];
; #pragma unroll
;     for (int i = 0; i < 2; ++i) { int R, C; stage_rc(tid * 16 + i * 8192, R, C); const int Rb = Epi::PERM ? ((R & ~31) + perm32(R & 31)) : R;
;         voffA[i] = (unsigned)(R * g.lda + C) * 2u; voffB[i] = (unsigned)(Rb * g.ldb + C) * 2u; }
;     const size_t kstep = (size_t)(BK * 2);
;     const size_t hstepA = (size_t)HALF * g.lda * 2, hstepB = (size_t)HALF * g.ldb * 2;
;     const size_t tstepA = 2 * hstepA, tstepB = 2 * hstepB;
;     const unsigned ldsw = (unsigned)wid * 1024u;
;     const int aoff = lds_byte(wr * 64 + fr, fq * 8), boff = lds_byte(wc * 32 + fr, fq * 8);
;     ...
;     Unit cur, nxt; int ui = 0;
;     if (!S.next(0, cur)) return;
;     f32x4 acc[2][2][4][2];
; #pragma unroll
;     for (int a = 0; a < 2; ++a)
; #pragma unroll
;         for (int b = 0; b < 2; ++b)
; #pragma unroll
;             for (int m = 0; m < 4; ++m)
; #pragma unroll
;                 for (int n = 0; n < 2; ++n) acc[a][b][m][n] = (f32x4){0.f, 0.f, 0.f, 0.f};
;     bf16x8 At[4][2], B0[2][2], B1[2][2];
;     const char* cA = (const char*)g.A + (size_t)cur.pm * tstepA; const char* cB = (const char*)g.Bt + (size_t)cur.pn * tstepB;
;     S.a_ready(cur);
;     if constexpr (SP2) {
;         PG8_STAGE(PG8_SB(0, 0), cB, voffB); PG8_STAGE(PG8_SB(0, 1), cB + hstepB, voffB); PG8_STAGE(PG8_SA(0, 0), cA, voffA); PG8_STAGE(PG8_SA(0, 1), cA + hstepA, voffA);
;         if (wr == 1) PG8_BAR;
;         PG8_WAIT_V(2); PG8_BAR;
;         PG8_STAGE(PG8_SB(1, 0), cB + kstep, voffB); PG8_STAGE(PG8_SA(1, 0), cA + kstep, voffA); PG8_STAGE(PG8_SB(1, 1), cB + hstepB + kstep, voffB);
;         PG8_WAIT_V(6); PG8_BAR;
;     } else {
;         PG8_STAGE(PG8_SB(0, 0), cB, voffB); PG8_STAGE(PG8_SA(0, 0), cA, voffA); PG8_STAGE(PG8_SB(0, 1), cB + hstepB, voffB); PG8_STAGE(PG8_SA(0, 1), cA + hstepA, voffA);
;         if (wr == 1) PG8_BAR;
;         PG8_WAIT_V(4); PG8_BAR;
.LBB0_269:
	s_andn2_b64 vcc, exec, s[0:1]
	v_readlane_b32 s0, v254, 0
	v_readlane_b32 s1, v254, 1
	s_nop 1
	v_cndmask_b32_e64 v0, 0, 1, s[0:1]
	v_cmp_ne_u32_e64 s[0:1], 1, v0
	s_nop 1
	v_writelane_b32 v255, s0, 49
	s_nop 1
	v_writelane_b32 v255, s1, 50
	s_cbranch_vccnz .LBB0_334
	s_load_dwordx2 s[6:7], s[82:83], 0xb8
	v_mov_b32_e32 v0, v1
	s_waitcnt lgkmcnt(0)
	v_readlane_b32 s0, v253, 21
	v_mbcnt_lo_u32_b32 v0, -1, v0
	v_mbcnt_hi_u32_b32 v0, -1, v0
	v_or_b32_e32 v0, s0, v0
	s_nop 0
	v_readfirstlane_b32 s0, v0
	v_mov_b32_e32 v0, v1
	s_andn2_b32 s0, s0, 63
	v_mbcnt_lo_u32_b32 v0, -1, v0
	v_mbcnt_hi_u32_b32 v0, -1, v0
	v_or_b32_e32 v16, s0, v0
	v_readlane_b32 s0, v255, 49
	v_readlane_b32 s1, v255, 50
	s_and_b64 vcc, exec, s[0:1]
	v_readfirstlane_b32 s8, v16
	s_cbranch_vccnz .LBB0_286
	v_lshlrev_b32_e32 v0, 4, v16
	v_add_u32_e32 v2, 0x2000, v0
	v_ashrrev_i32_e32 v3, 31, v2
	v_lshrrev_b32_e32 v3, 22, v3
	v_add_u32_e32 v3, v2, v3
	v_ashrrev_i32_e32 v10, 10, v3
	v_mul_i32_i24_e32 v3, 0x400, v10
	v_sub_u32_e32 v2, v2, v3
	v_lshrrev_b32_e32 v3, 4, v2
	v_bitop3_b32 v2, v3, v2, 32 bitop3:0x6c
	v_ashrrev_i32_e32 v3, 31, v2
	s_add_u32 s2, s6, 0x1ed90000
	v_lshrrev_b32_e32 v3, 26, v3
	s_addc_u32 s22, s7, 0
	s_mul_i32 s0, s78, 0x5800000
	v_add_u32_e32 v3, v2, v3
	v_lshlrev_b32_e32 v4, 3, v10
	s_add_u32 s0, s6, s0
	v_ashrrev_i32_e32 v11, 6, v3
	v_and_b32_e32 v4, -16, v4
	s_addc_u32 s1, s7, 0
	v_add_u32_e32 v4, v11, v4
	s_add_u32 s36, s0, 0x190000
	v_and_b32_e32 v5, 3, v11
	s_mov_b32 s0, 0xfffe0
	v_lshrrev_b32_e32 v6, 2, v4
	v_lshlrev_b32_e32 v7, 1, v4
	v_and_or_b32 v5, v4, s0, v5
	v_and_b32_e32 v6, 4, v6
	v_and_b32_e32 v7, 24, v7
	v_and_b32_e32 v3, 0xc0, v3
	v_or3_b32 v5, v5, v6, v7
	v_sub_u32_e32 v2, v2, v3
	v_mov_b32_e32 v7, 1
	v_lshlrev_b32_e32 v6, 5, v10
	v_ashrrev_i16_sdwa v2, v7, sext(v2) dst_sel:DWORD dst_unused:UNUSED_PAD src0_sel:DWORD src1_sel:BYTE_0
	v_and_b32_e32 v6, 32, v6
	v_bfe_i32 v12, v2, 0, 16
	v_add_lshl_u32 v2, v6, v12, 1
	s_waitcnt vmcnt(0)
	v_lshl_add_u32 v130, v5, 7, v2
	v_lshl_add_u32 v132, v4, 12, v2
	v_bfe_i32 v2, v16, 27, 1
	v_lshrrev_b32_e32 v2, 22, v2
	v_add_u32_e32 v2, v0, v2
	v_and_b32_e32 v2, 0xfffffc00, v2
	v_sub_u32_e32 v0, v0, v2
	v_lshrrev_b32_e32 v2, 4, v0
	v_ashrrev_i32_e32 v3, 31, v16
	v_bitop3_b32 v0, v2, v0, 32 bitop3:0x6c
	v_lshrrev_b32_e32 v3, 26, v3
	v_ashrrev_i32_e32 v2, 31, v0
	v_add_u32_e32 v3, v16, v3
	v_lshrrev_b32_e32 v2, 26, v2
	v_ashrrev_i32_e32 v14, 6, v3
	v_add_u32_e32 v2, v0, v2
	v_lshlrev_b32_e32 v3, 3, v14
	v_ashrrev_i32_e32 v13, 6, v2
	v_and_b32_e32 v3, -16, v3
	v_add_u32_e32 v3, v13, v3
	v_and_b32_e32 v4, 3, v13
	v_lshrrev_b32_e32 v5, 2, v3
	v_lshlrev_b32_e32 v6, 1, v3
	v_and_b32_e32 v2, 0xc0, v2
	s_addc_u32 s37, s1, 0
	s_ashr_i32 s9, s8, 6
	v_and_or_b32 v4, v3, s0, v4
	v_and_b32_e32 v5, 4, v5
	v_and_b32_e32 v6, 24, v6
	v_sub_u32_e32 v0, v0, v2
	s_ashr_i32 s10, s8, 8
	s_lshl_b32 s40, s9, 10
	v_or3_b32 v4, v4, v5, v6
	v_lshlrev_b32_e32 v5, 5, v14
	v_ashrrev_i16_sdwa v0, v7, sext(v0) dst_sel:DWORD dst_unused:UNUSED_PAD src0_sel:DWORD src1_sel:BYTE_0
	v_readlane_b32 s0, v254, 47
	v_and_b32_e32 v5, 32, v5
	v_bfe_i32 v15, v0, 0, 16
	v_readlane_b32 s1, v254, 48
	s_add_u32 s18, s36, s0
	v_add_lshl_u32 v2, v5, v15, 1
	s_addc_u32 s19, s37, s1
	s_add_i32 s41, s40, 0
	v_lshl_add_u32 v0, v4, 7, v2
	s_add_i32 m0, s41, 0x10000
	v_lshl_add_u32 v134, v3, 12, v2
	global_load_lds_dwordx4 v0, s[18:19]
	s_add_i32 m0, s41, 0x12000
	s_add_u32 s0, s18, 0x4000
	global_load_lds_dwordx4 v130, s[18:19]
	s_addc_u32 s1, s19, 0
	s_add_i32 m0, s41, 0x14000
	v_mov_b32_e32 v131, v1
	global_load_lds_dwordx4 v0, s[0:1]
	s_add_i32 m0, s41, 0x16000
	v_mov_b32_e32 v135, v1
	global_load_lds_dwordx4 v130, s[0:1]
	v_readlane_b32 s0, v254, 56
	v_readlane_b32 s1, v254, 57
	s_add_u32 s20, s2, s0
	s_addc_u32 s21, s22, s1
	s_add_i32 s42, s41, 0x2000
	s_mov_b32 m0, s41
	s_add_u32 s0, s20, 0x80000
	global_load_lds_dwordx4 v134, s[20:21]
	s_mov_b32 m0, s42
	s_addc_u32 s1, s21, 0
	s_add_i32 s43, s41, 0x4000
	global_load_lds_dwordx4 v132, s[20:21]
	s_mov_b32 m0, s43
	s_add_i32 s44, s41, 0x6000
	global_load_lds_dwordx4 v134, s[0:1]
	s_mov_b32 m0, s44
	v_mov_b32_e32 v133, v1
	global_load_lds_dwordx4 v132, s[0:1]
	s_cmp_eq_u32 s10, 1
	v_lshl_add_u64 v[8:9], s[18:19], 0, v[0:1]
	v_lshl_add_u64 v[6:7], s[18:19], 0, v[130:131]
	v_lshl_add_u64 v[2:3], s[20:21], 0, v[134:135]
	s_cselect_b64 s[0:1], -1, 0
	s_cmp_lg_u32 s10, 1
	v_lshl_add_u64 v[4:5], s[20:21], 0, v[132:133]
	s_cbranch_scc1 .LBB0_273
	s_barrier
.LBB0_273:
	s_add_u32 s6, s6, 0x22d90000
	v_lshrrev_b32_e32 v18, 1, v16
	s_addc_u32 s7, s7, 0
	v_and_b32_e32 v18, 24, v18
	s_lshl_b32 s9, s9, 5
	v_and_b32_e32 v17, 15, v16
	v_lshlrev_b32_e32 v19, 1, v18
	v_lshlrev_b32_e32 v16, 2, v16
	s_and_b32 s12, s9, 0x60
	s_add_i32 m0, s41, 0x18000
	s_mov_b64 s[100:101], 0x8000
	v_lshl_add_u64 v[8:9], v[8:9], 0, s[100:101]
	v_lshl_or_b32 v142, s10, 6, v17
	v_lshl_or_b32 v17, v17, 6, v19
	s_lshl_b32 s10, s10, 13
	v_and_b32_e32 v16, 32, v16
	s_lshl_b32 s9, s12, 7
	s_waitcnt vmcnt(2)
	s_barrier
	global_load_lds_dwordx4 v[8:9], off
	v_lshl_add_u64 v[6:7], v[6:7], 0, s[100:101]
	s_add_i32 m0, s41, 0x1a000
	s_add_i32 s45, s41, 0x8000
	s_add_i32 s46, s41, 0xa000
	v_bitop3_b32 v19, v17, s10, v16 bitop3:0xde
	global_load_lds_dwordx4 v[6:7], off
	v_lshl_add_u64 v[2:3], v[2:3], 0, s[30:31]
	s_mov_b32 m0, s45
	s_add_u32 s10, s18, 0xc000
	global_load_lds_dwordx4 v[2:3], off
	v_lshl_add_u64 v[2:3], v[4:5], 0, s[30:31]
	s_mov_b32 m0, s46
	s_addc_u32 s11, s19, 0
	global_load_lds_dwordx4 v[2:3], off
	s_add_i32 m0, s41, 0x1c000
	v_lshl_add_u64 v[2:3], s[10:11], 0, v[0:1]
	global_load_lds_dwordx4 v[2:3], off
	v_lshl_add_u64 v[2:3], s[10:11], 0, v[130:131]
	s_add_i32 m0, s41, 0x1e000
	s_cmpk_lt_u32 s8, 0x100
	global_load_lds_dwordx4 v[2:3], off
	v_lshlrev_b32_e32 v2, 15, v10
	v_and_b32_e32 v2, 0xffff0000, v2
	v_lshl_add_u32 v2, v11, 12, v2
	v_and_b32_e32 v3, 1, v10
	v_lshl_or_b32 v2, v3, 6, v2
	v_lshl_add_u32 v136, v12, 1, v2
	v_lshlrev_b32_e32 v2, 15, v14
	v_and_b32_e32 v2, 0xffff0000, v2
	s_waitcnt vmcnt(6)
	v_lshl_add_u32 v2, v13, 12, v2
	v_and_b32_e32 v3, 1, v14
	v_lshl_or_b32 v2, v3, 6, v2
	v_readlane_b32 s10, v254, 54
	v_bitop3_b32 v143, v17, s9, v16 bitop3:0xde
	s_cselect_b64 s[8:9], -1, 0
	v_or_b32_e32 v144, s12, v18
	v_mov_b32_e32 v137, v1
	v_lshl_add_u32 v138, v15, 1, v2
	v_mov_b32_e32 v139, v1
	s_mov_b32 s47, 0
	v_add_u32_e32 v145, 0, v19
	v_readlane_b32 s26, v254, 46
	s_mov_b32 s27, s10
	s_barrier
	v_readlane_b32 s11, v254, 55
	s_branch .LBB0_276

; #define PG8_STAGE(bufoff, gbase, voff) do { _Pragma("unroll") for (int _i = 0; _i < 2; ++_i) \
;         __builtin_amdgcn_global_load_lds((const unsigned*)((const char*)(gbase) + (voff)[_i]), (PG8_LAS unsigned*)(lds + (bufoff) + ldsw + _i * 8192), 16, 0, 0); } while (0)
; #define PG8_LDA(dst, b, h) do { _Pragma("unroll") for (int m = 0; m < 4; ++m) _Pragma("unroll") for (int k = 0; k < 2; ++k) dst[m][k] = *(const PG8_LAS bf16x8*)(lds + PG8_SA(b, h) + aoff + m * 2048 + k * 1024); } while (0)
; #define PG8_LDB(dst, b, h) do { _Pragma("unroll") for (int n = 0; n < 2; ++n) _Pragma("unroll") for (int k = 0; k < 2; ++k) dst[n][k] = *(const PG8_LAS bf16x8*)(lds + PG8_SB(b, h) + boff + n * 2048 + k * 1024); } while (0)
; #define PG8_MMA(ai, bj, At, Bt) do { __builtin_amdgcn_s_setprio(1); _Pragma("unroll") for (int m = 0; m < 4; ++m) _Pragma("unroll") for (int n = 0; n < 2; ++n) _Pragma("unroll") for (int k = 0; k < 2; ++k) \
;         acc[ai][bj][m][n] = __builtin_amdgcn_mfma_f32_16x16x32_bf16(Bt[n][k], At[m][k], acc[ai][bj][m][n], 0, 0, 0); __builtin_amdgcn_s_setprio(0); } while (0)
; #define PG8_WAIT_V(n) asm volatile("s_waitcnt vmcnt(" #n ")" ::: "memory")
; template <class Epi, class Sched, bool ALIGN_EPI = false, bool SP2 = false>
; __device__ __forceinline__ void gemm_phase(PG8_LAS unsigned char* lds, const Gemm g, const Sched& S, const Epi& E, int wave_s) {
;     ...
;         const bool has_next = S.next(ui + 1, nxt);
;         const char* nA = has_next ? (const char*)g.A + (size_t)nxt.pm * tstepA : cA; const char* nB = has_next ? (const char*)g.Bt + (size_t)nxt.pn * tstepB : cB;
;         for (int t = 0; t < nt; t += 2) {
;             const bool last = (t == nt - 2);
;             const char* a1 = cA + (size_t)(t + 1) * kstep;
;             const char* a2 = last ? nA : cA + (size_t)(t + 2) * kstep; const char* b2 = last ? nB : cB + (size_t)(t + 2) * kstep;
;             const char* a3 = a2 + kstep; const char* b3 = b2 + kstep;
;             if (last && has_next) S.a_ready(nxt);
;             if constexpr (Epi::HAS_MID) { if (t == nt / 2) E.mid(acc, cur, wr, wc, fr, fq); }
;             if constexpr (SP2) {
;             PG8_LDB(B0, 0, 0); PG8_LDB(B1, 0, 1); PG8_SCHED; PG8_LDA(At, 0, 0); PG8_STAGE(PG8_SA(1, 1), a1 + hstepA, voffA);
;             PG8_WAIT_V(8); PG8_WAIT_L(0); PG8_BAR; PG8_MMA(0, 0, At, B0); PG8_MMA(0, 1, At, B1); PG8_BAR; PG8_SCHED;
.LBB0_278:
	s_ashr_i32 s13, s12, 31
	s_lshl_b64 s[14:15], s[12:13], 20
	s_add_u32 s14, s2, s14
	s_addc_u32 s15, s22, s15
	s_and_b64 s[16:17], s[38:39], exec
	s_cselect_b32 s13, s15, s21
	s_cselect_b32 s33, s14, s20
	s_ashr_i32 s11, s10, 31
	s_lshl_b64 s[16:17], s[10:11], 20
	s_add_u32 s16, s36, s16
	s_addc_u32 s17, s37, s17
	s_and_b64 s[24:25], s[38:39], exec
	s_cselect_b32 s11, s17, s19
	s_cselect_b32 s48, s16, s18
	s_add_u32 s49, s18, 0x10000
	s_addc_u32 s50, s19, 0
	s_add_u32 s18, s20, 0x80080
	v_mov_b32_e32 v2, 0
	s_addc_u32 s19, s21, 0
	s_mov_b32 s51, -2
	v_mov_b32_e32 v3, v2
	v_mov_b32_e32 v4, v2
	v_mov_b32_e32 v5, v2
	v_mov_b32_e32 v10, v2
	v_mov_b32_e32 v11, v2
	v_mov_b32_e32 v12, v2
	v_mov_b32_e32 v13, v2
	v_mov_b32_e32 v18, v2
	v_mov_b32_e32 v19, v2
	v_mov_b32_e32 v20, v2
	v_mov_b32_e32 v21, v2
	v_mov_b32_e32 v26, v2
	v_mov_b32_e32 v27, v2
	v_mov_b32_e32 v28, v2
	v_mov_b32_e32 v29, v2
	v_mov_b32_e32 v34, v2
	v_mov_b32_e32 v35, v2
	v_mov_b32_e32 v36, v2
	v_mov_b32_e32 v37, v2
	v_mov_b32_e32 v42, v2
	v_mov_b32_e32 v43, v2
	v_mov_b32_e32 v44, v2
	v_mov_b32_e32 v45, v2
	v_mov_b32_e32 v50, v2
	v_mov_b32_e32 v51, v2
	v_mov_b32_e32 v52, v2
	v_mov_b32_e32 v53, v2
	v_mov_b32_e32 v58, v2
	v_mov_b32_e32 v59, v2
	v_mov_b32_e32 v60, v2
	v_mov_b32_e32 v61, v2
	v_mov_b32_e32 v6, v2
	v_mov_b32_e32 v7, v2
	v_mov_b32_e32 v8, v2
	v_mov_b32_e32 v9, v2
	v_mov_b32_e32 v14, v2
	v_mov_b32_e32 v15, v2
	v_mov_b32_e32 v16, v2
	v_mov_b32_e32 v17, v2
	v_mov_b32_e32 v22, v2
	v_mov_b32_e32 v23, v2
	v_mov_b32_e32 v24, v2
	v_mov_b32_e32 v25, v2
	v_mov_b32_e32 v30, v2
	v_mov_b32_e32 v31, v2
	v_mov_b32_e32 v32, v2
	v_mov_b32_e32 v33, v2
	v_mov_b32_e32 v38, v2
	v_mov_b32_e32 v39, v2
	v_mov_b32_e32 v40, v2
	v_mov_b32_e32 v41, v2
	v_mov_b32_e32 v46, v2
	v_mov_b32_e32 v47, v2
	v_mov_b32_e32 v48, v2
	v_mov_b32_e32 v49, v2
	v_mov_b32_e32 v54, v2
	v_mov_b32_e32 v55, v2
	v_mov_b32_e32 v56, v2
	v_mov_b32_e32 v57, v2
	v_mov_b32_e32 v62, v2
	v_mov_b32_e32 v63, v2
	v_mov_b32_e32 v64, v2
	v_mov_b32_e32 v65, v2
	v_mov_b32_e32 v66, v2
	v_mov_b32_e32 v67, v2
	v_mov_b32_e32 v68, v2
	v_mov_b32_e32 v69, v2
	v_mov_b32_e32 v74, v2
	v_mov_b32_e32 v75, v2
	v_mov_b32_e32 v76, v2
	v_mov_b32_e32 v77, v2
	v_mov_b32_e32 v82, v2
	v_mov_b32_e32 v83, v2
	v_mov_b32_e32 v84, v2
	v_mov_b32_e32 v85, v2
	v_mov_b32_e32 v90, v2
	v_mov_b32_e32 v91, v2
	v_mov_b32_e32 v92, v2
	v_mov_b32_e32 v93, v2
	v_mov_b32_e32 v98, v2
	v_mov_b32_e32 v99, v2
	v_mov_b32_e32 v100, v2
	v_mov_b32_e32 v101, v2
	v_mov_b32_e32 v106, v2
	v_mov_b32_e32 v107, v2
	v_mov_b32_e32 v108, v2
	v_mov_b32_e32 v109, v2
	v_mov_b32_e32 v114, v2
	v_mov_b32_e32 v115, v2
	v_mov_b32_e32 v116, v2
	v_mov_b32_e32 v117, v2
	v_mov_b32_e32 v122, v2
	v_mov_b32_e32 v123, v2
	v_mov_b32_e32 v124, v2
	v_mov_b32_e32 v125, v2
	v_mov_b32_e32 v70, v2
	v_mov_b32_e32 v71, v2
	v_mov_b32_e32 v72, v2
	v_mov_b32_e32 v73, v2
	v_mov_b32_e32 v78, v2
	v_mov_b32_e32 v79, v2
	v_mov_b32_e32 v80, v2
	v_mov_b32_e32 v81, v2
	v_mov_b32_e32 v86, v2
	v_mov_b32_e32 v87, v2
	v_mov_b32_e32 v88, v2
	v_mov_b32_e32 v89, v2
	v_mov_b32_e32 v94, v2
	v_mov_b32_e32 v95, v2
	v_mov_b32_e32 v96, v2
	v_mov_b32_e32 v97, v2
	v_mov_b32_e32 v102, v2
	v_mov_b32_e32 v103, v2
	v_mov_b32_e32 v104, v2
	v_mov_b32_e32 v105, v2
	v_mov_b32_e32 v110, v2
	v_mov_b32_e32 v111, v2
	v_mov_b32_e32 v112, v2
	v_mov_b32_e32 v113, v2
	v_mov_b32_e32 v118, v2
	v_mov_b32_e32 v119, v2
	v_mov_b32_e32 v120, v2
	v_mov_b32_e32 v121, v2
	v_mov_b32_e32 v126, v2
	v_mov_b32_e32 v127, v2
	v_mov_b32_e32 v128, v2
	v_mov_b32_e32 v129, v2
.LBB0_279:
	s_add_u32 s20, s18, 0xfff80080
	s_addc_u32 s21, s19, -1
	s_add_i32 s34, 0, 0x10000
	s_cmp_eq_u32 s51, 28
	s_cselect_b32 s25, s13, s21
	s_cselect_b32 s24, s33, s20
	v_add_u32_e32 v140, s34, v143
	s_cselect_b32 s21, s11, s50
	s_cselect_b32 s20, s48, s49
	s_add_i32 s54, 0, 0x14000
	ds_read_b128 v[146:149], v140
	ds_read_b128 v[150:153], v140 offset:1024
	ds_read_b128 v[154:157], v140 offset:2048
	ds_read_b128 v[158:161], v140 offset:3072
	v_add_u32_e32 v140, s54, v143
	ds_read_b128 v[162:165], v140
	ds_read_b128 v[166:169], v140 offset:1024
	ds_read_b128 v[176:179], v140 offset:2048
	ds_read_b128 v[180:183], v140 offset:3072
	v_lshl_add_u64 v[140:141], s[18:19], 0, v[138:139]
	s_add_i32 m0, s41, 0xc000
	ds_read_b128 v[184:187], v145
	ds_read_b128 v[188:191], v145 offset:1024
	ds_read_b128 v[192:195], v145 offset:2048
	ds_read_b128 v[196:199], v145 offset:3072
	ds_read_b128 v[208:211], v145 offset:4096
	ds_read_b128 v[212:215], v145 offset:5120
	ds_read_b128 v[216:219], v145 offset:6144
	ds_read_b128 v[220:223], v145 offset:7168
	global_load_lds_dwordx4 v[140:141], off
	v_lshl_add_u64 v[140:141], s[18:19], 0, v[136:137]
	s_add_i32 m0, s41, 0xe000
	s_nop 0
	global_load_lds_dwordx4 v[140:141], off
	s_waitcnt vmcnt(8)
	s_waitcnt lgkmcnt(0)
	s_barrier
; #define PG8_STAGE(bufoff, gbase, voff) do { _Pragma("unroll") for (int _i = 0; _i < 2; ++_i) \
;         __builtin_amdgcn_global_load_lds((const unsigned*)((const char*)(gbase) + (voff)[_i]), (PG8_LAS unsigned*)(lds + (bufoff) + ldsw + _i * 8192), 16, 0, 0); } while (0)
; #define PG8_LDA(dst, b, h) do { _Pragma("unroll") for (int m = 0; m < 4; ++m) _Pragma("unroll") for (int k = 0; k < 2; ++k) dst[m][k] = *(const PG8_LAS bf16x8*)(lds + PG8_SA(b, h) + aoff + m * 2048 + k * 1024); } while (0)
; #define PG8_MMA(ai, bj, At, Bt) do { __builtin_amdgcn_s_setprio(1); _Pragma("unroll") for (int m = 0; m < 4; ++m) _Pragma("unroll") for (int n = 0; n < 2; ++n) _Pragma("unroll") for (int k = 0; k < 2; ++k) \
;         acc[ai][bj][m][n] = __builtin_amdgcn_mfma_f32_16x16x32_bf16(Bt[n][k], At[m][k], acc[ai][bj][m][n], 0, 0, 0); __builtin_amdgcn_s_setprio(0); } while (0)
; #define PG8_WAIT_V(n) asm volatile("s_waitcnt vmcnt(" #n ")" ::: "memory")
; #define PG8_WAIT_L(n) asm volatile("s_waitcnt lgkmcnt(" #n ")" ::: "memory")
; #define PG8_BAR __builtin_amdgcn_s_barrier()
; #define PG8_SCHED __builtin_amdgcn_sched_barrier(0)
; template <class Epi, class Sched, bool ALIGN_EPI = false, bool SP2 = false>
; __device__ __forceinline__ void gemm_phase(PG8_LAS unsigned char* lds, const Gemm g, const Sched& S, const Epi& E, int wave_s) {
;     ...
;             PG8_WAIT_V(8); PG8_WAIT_L(0); PG8_BAR; PG8_MMA(0, 0, At, B0); PG8_MMA(0, 1, At, B1); PG8_BAR; PG8_SCHED;
;             PG8_LDA(At, 0, 1); PG8_STAGE(PG8_SB(0, 0), b2, voffB); PG8_STAGE(PG8_SB(0, 1), b2 + hstepB, voffB); PG8_STAGE(PG8_SA(0, 0), a2, voffA);
;             PG8_WAIT_V(8); PG8_WAIT_L(0); PG8_BAR; PG8_MMA(1, 0, At, B0); PG8_MMA(1, 1, At, B1); PG8_BAR; PG8_SCHED;
	s_setprio 1
	s_waitcnt lgkmcnt(0)
	v_mfma_f32_16x16x32_bf16 v[126:129], v[146:149], v[184:187], v[126:129]
	v_mfma_f32_16x16x32_bf16 v[118:121], v[154:157], v[184:187], v[118:121]
	v_mfma_f32_16x16x32_bf16 v[110:113], v[146:149], v[192:195], v[110:113]
	v_mfma_f32_16x16x32_bf16 v[102:105], v[154:157], v[192:195], v[102:105]
	v_mfma_f32_16x16x32_bf16 v[94:97], v[146:149], v[208:211], v[94:97]
	v_mfma_f32_16x16x32_bf16 v[86:89], v[154:157], v[208:211], v[86:89]
	v_mfma_f32_16x16x32_bf16 v[78:81], v[146:149], v[216:219], v[78:81]
	v_mfma_f32_16x16x32_bf16 v[70:73], v[154:157], v[216:219], v[70:73]
	v_mfma_f32_16x16x32_bf16 v[126:129], v[150:153], v[188:191], v[126:129]
	v_mfma_f32_16x16x32_bf16 v[118:121], v[158:161], v[188:191], v[118:121]
	v_mfma_f32_16x16x32_bf16 v[110:113], v[150:153], v[196:199], v[110:113]
	v_mfma_f32_16x16x32_bf16 v[102:105], v[158:161], v[196:199], v[102:105]
	v_mfma_f32_16x16x32_bf16 v[94:97], v[150:153], v[212:215], v[94:97]
	v_mfma_f32_16x16x32_bf16 v[86:89], v[158:161], v[212:215], v[86:89]
	v_mfma_f32_16x16x32_bf16 v[78:81], v[150:153], v[220:223], v[78:81]
	v_mfma_f32_16x16x32_bf16 v[70:73], v[158:161], v[220:223], v[70:73]
	s_setprio 0
	s_setprio 1
	v_mfma_f32_16x16x32_bf16 v[122:125], v[162:165], v[184:187], v[122:125]
	v_mfma_f32_16x16x32_bf16 v[114:117], v[176:179], v[184:187], v[114:117]
	v_mfma_f32_16x16x32_bf16 v[106:109], v[162:165], v[192:195], v[106:109]
	v_mfma_f32_16x16x32_bf16 v[98:101], v[176:179], v[192:195], v[98:101]
	v_mfma_f32_16x16x32_bf16 v[90:93], v[162:165], v[208:211], v[90:93]
	v_mfma_f32_16x16x32_bf16 v[82:85], v[176:179], v[208:211], v[82:85]
	v_mfma_f32_16x16x32_bf16 v[74:77], v[162:165], v[216:219], v[74:77]
	v_mfma_f32_16x16x32_bf16 v[66:69], v[176:179], v[216:219], v[66:69]
	v_mfma_f32_16x16x32_bf16 v[122:125], v[166:169], v[188:191], v[122:125]
	v_mfma_f32_16x16x32_bf16 v[114:117], v[180:183], v[188:191], v[114:117]
	v_mfma_f32_16x16x32_bf16 v[106:109], v[166:169], v[196:199], v[106:109]
	v_mfma_f32_16x16x32_bf16 v[98:101], v[180:183], v[196:199], v[98:101]
	v_mfma_f32_16x16x32_bf16 v[90:93], v[166:169], v[212:215], v[90:93]
	v_mfma_f32_16x16x32_bf16 v[82:85], v[180:183], v[212:215], v[82:85]
	v_mfma_f32_16x16x32_bf16 v[74:77], v[166:169], v[220:223], v[74:77]
	v_mfma_f32_16x16x32_bf16 v[66:69], v[180:183], v[220:223], v[66:69]
	s_setprio 0
	s_barrier
	s_add_i32 s34, s34, s40
	v_lshl_add_u64 v[140:141], s[20:21], 0, v[0:1]
	s_mov_b32 m0, s34
	ds_read_b128 v[184:187], v145 offset:16384
	ds_read_b128 v[188:191], v145 offset:17408
	ds_read_b128 v[192:195], v145 offset:18432
	ds_read_b128 v[196:199], v145 offset:19456
	ds_read_b128 v[208:211], v145 offset:20480
	ds_read_b128 v[212:215], v145 offset:21504
	ds_read_b128 v[216:219], v145 offset:22528
	ds_read_b128 v[220:223], v145 offset:23552
	global_load_lds_dwordx4 v[140:141], off
	s_add_i32 m0, s34, 0x2000
	s_add_u32 s34, s20, 0x4000
	v_lshl_add_u64 v[170:171], s[20:21], 0, v[130:131]
	s_addc_u32 s35, s21, 0
	s_add_i32 s54, s54, s40
	global_load_lds_dwordx4 v[170:171], off
	v_lshl_add_u64 v[200:201], s[34:35], 0, v[0:1]
	s_mov_b32 m0, s54
	v_lshl_add_u64 v[224:225], s[24:25], 0, v[132:133]
	global_load_lds_dwordx4 v[200:201], off
	v_lshl_add_u64 v[200:201], s[34:35], 0, v[130:131]
	s_add_i32 m0, s54, 0x2000
	s_nop 0
	global_load_lds_dwordx4 v[200:201], off
	v_lshl_add_u64 v[200:201], s[24:25], 0, v[134:135]
	s_mov_b32 m0, s41
	s_nop 0
	global_load_lds_dwordx4 v[200:201], off
	s_mov_b32 m0, s42
	s_nop 0
	global_load_lds_dwordx4 v[224:225], off
	s_waitcnt vmcnt(8)
	s_waitcnt lgkmcnt(0)
	s_barrier
	s_setprio 1
	s_waitcnt lgkmcnt(0)
	v_mfma_f32_16x16x32_bf16 v[62:65], v[146:149], v[184:187], v[62:65]
	v_mfma_f32_16x16x32_bf16 v[54:57], v[154:157], v[184:187], v[54:57]
	v_mfma_f32_16x16x32_bf16 v[46:49], v[146:149], v[192:195], v[46:49]
	v_mfma_f32_16x16x32_bf16 v[38:41], v[154:157], v[192:195], v[38:41]
	v_mfma_f32_16x16x32_bf16 v[30:33], v[146:149], v[208:211], v[30:33]
	v_mfma_f32_16x16x32_bf16 v[22:25], v[154:157], v[208:211], v[22:25]
	v_mfma_f32_16x16x32_bf16 v[14:17], v[146:149], v[216:219], v[14:17]
	v_mfma_f32_16x16x32_bf16 v[6:9], v[154:157], v[216:219], v[6:9]
	v_mfma_f32_16x16x32_bf16 v[62:65], v[150:153], v[188:191], v[62:65]
	v_mfma_f32_16x16x32_bf16 v[54:57], v[158:161], v[188:191], v[54:57]
	v_mfma_f32_16x16x32_bf16 v[46:49], v[150:153], v[196:199], v[46:49]
	v_mfma_f32_16x16x32_bf16 v[38:41], v[158:161], v[196:199], v[38:41]
	v_mfma_f32_16x16x32_bf16 v[30:33], v[150:153], v[212:215], v[30:33]
	v_mfma_f32_16x16x32_bf16 v[22:25], v[158:161], v[212:215], v[22:25]
	v_mfma_f32_16x16x32_bf16 v[14:17], v[150:153], v[220:223], v[14:17]
	v_mfma_f32_16x16x32_bf16 v[6:9], v[158:161], v[220:223], v[6:9]
	s_setprio 0
	s_setprio 1
	v_mfma_f32_16x16x32_bf16 v[58:61], v[162:165], v[184:187], v[58:61]
	v_mfma_f32_16x16x32_bf16 v[50:53], v[176:179], v[184:187], v[50:53]
	v_mfma_f32_16x16x32_bf16 v[42:45], v[162:165], v[192:195], v[42:45]
	v_mfma_f32_16x16x32_bf16 v[34:37], v[176:179], v[192:195], v[34:37]
	v_mfma_f32_16x16x32_bf16 v[26:29], v[162:165], v[208:211], v[26:29]
	v_mfma_f32_16x16x32_bf16 v[18:21], v[176:179], v[208:211], v[18:21]
	v_mfma_f32_16x16x32_bf16 v[10:13], v[162:165], v[216:219], v[10:13]
	v_mfma_f32_16x16x32_bf16 v[2:5], v[176:179], v[216:219], v[2:5]
	v_mfma_f32_16x16x32_bf16 v[58:61], v[166:169], v[188:191], v[58:61]
	v_mfma_f32_16x16x32_bf16 v[50:53], v[180:183], v[188:191], v[50:53]
	v_mfma_f32_16x16x32_bf16 v[42:45], v[166:169], v[196:199], v[42:45]
	v_mfma_f32_16x16x32_bf16 v[34:37], v[180:183], v[196:199], v[34:37]
	v_mfma_f32_16x16x32_bf16 v[26:29], v[166:169], v[212:215], v[26:29]
	v_mfma_f32_16x16x32_bf16 v[18:21], v[180:183], v[212:215], v[18:21]
	v_mfma_f32_16x16x32_bf16 v[10:13], v[166:169], v[220:223], v[10:13]
	v_mfma_f32_16x16x32_bf16 v[2:5], v[180:183], v[220:223], v[2:5]
	s_setprio 0
	s_barrier
; #define PG8_STAGE(bufoff, gbase, voff) do { _Pragma("unroll") for (int _i = 0; _i < 2; ++_i) \
;         __builtin_amdgcn_global_load_lds((const unsigned*)((const char*)(gbase) + (voff)[_i]), (PG8_LAS unsigned*)(lds + (bufoff) + ldsw + _i * 8192), 16, 0, 0); } while (0)
; #define PG8_LDA(dst, b, h) do { _Pragma("unroll") for (int m = 0; m < 4; ++m) _Pragma("unroll") for (int k = 0; k < 2; ++k) dst[m][k] = *(const PG8_LAS bf16x8*)(lds + PG8_SA(b, h) + aoff + m * 2048 + k * 1024); } while (0)
; #define PG8_LDB(dst, b, h) do { _Pragma("unroll") for (int n = 0; n < 2; ++n) _Pragma("unroll") for (int k = 0; k < 2; ++k) dst[n][k] = *(const PG8_LAS bf16x8*)(lds + PG8_SB(b, h) + boff + n * 2048 + k * 1024); } while (0)
; #define PG8_MMA(ai, bj, At, Bt) do { __builtin_amdgcn_s_setprio(1); _Pragma("unroll") for (int m = 0; m < 4; ++m) _Pragma("unroll") for (int n = 0; n < 2; ++n) _Pragma("unroll") for (int k = 0; k < 2; ++k) \
;         acc[ai][bj][m][n] = __builtin_amdgcn_mfma_f32_16x16x32_bf16(Bt[n][k], At[m][k], acc[ai][bj][m][n], 0, 0, 0); __builtin_amdgcn_s_setprio(0); } while (0)
; #define PG8_WAIT_V(n) asm volatile("s_waitcnt vmcnt(" #n ")" ::: "memory")
; #define PG8_WAIT_L(n) asm volatile("s_waitcnt lgkmcnt(" #n ")" ::: "memory")
; #define PG8_BAR __builtin_amdgcn_s_barrier()
; #define PG8_SCHED __builtin_amdgcn_sched_barrier(0)
; template <class Epi, class Sched, bool ALIGN_EPI = false, bool SP2 = false>
; __device__ __forceinline__ void gemm_phase(PG8_LAS unsigned char* lds, const Gemm g, const Sched& S, const Epi& E, int wave_s) {
;     ...
;             PG8_LDB(B0, 1, 0); PG8_LDB(B1, 1, 1); PG8_SCHED; PG8_LDA(At, 1, 0); PG8_STAGE(PG8_SA(0, 1), a2 + hstepA, voffA);
;             PG8_WAIT_V(8); PG8_WAIT_L(0); PG8_BAR; PG8_MMA(0, 0, At, B0); PG8_MMA(0, 1, At, B1); PG8_BAR; PG8_SCHED;
	s_add_i32 s34, 0, 0x18000
	s_add_i32 s35, 0, 0x1c000
	v_add_u32_e32 v158, s34, v143
	v_add_u32_e32 v180, s35, v143
	ds_read_b128 v[146:149], v158
	ds_read_b128 v[150:153], v158 offset:1024
	ds_read_b128 v[154:157], v158 offset:2048
	ds_read_b128 v[158:161], v158 offset:3072
	ds_read_b128 v[162:165], v180
	ds_read_b128 v[166:169], v180 offset:1024
	ds_read_b128 v[176:179], v180 offset:2048
	ds_read_b128 v[180:183], v180 offset:3072
	s_add_u32 s24, s24, 0x80000
	s_addc_u32 s25, s25, 0
	s_mov_b32 m0, s43
	v_lshl_add_u64 v[226:227], s[24:25], 0, v[134:135]
	ds_read_b128 v[184:187], v145 offset:32768
	ds_read_b128 v[188:191], v145 offset:33792
	ds_read_b128 v[192:195], v145 offset:34816
	ds_read_b128 v[196:199], v145 offset:35840
	ds_read_b128 v[208:211], v145 offset:36864
	ds_read_b128 v[212:215], v145 offset:37888
	ds_read_b128 v[216:219], v145 offset:38912
	ds_read_b128 v[220:223], v145 offset:39936
	global_load_lds_dwordx4 v[226:227], off
	v_lshl_add_u64 v[226:227], s[24:25], 0, v[132:133]
	s_mov_b32 m0, s44
	s_nop 0
	global_load_lds_dwordx4 v[226:227], off
	s_waitcnt vmcnt(8)
	s_waitcnt lgkmcnt(0)
	s_barrier
	s_setprio 1
	s_waitcnt lgkmcnt(0)
	v_mfma_f32_16x16x32_bf16 v[126:129], v[146:149], v[184:187], v[126:129]
	v_mfma_f32_16x16x32_bf16 v[118:121], v[154:157], v[184:187], v[118:121]
	v_mfma_f32_16x16x32_bf16 v[110:113], v[146:149], v[192:195], v[110:113]
	v_mfma_f32_16x16x32_bf16 v[102:105], v[154:157], v[192:195], v[102:105]
	v_mfma_f32_16x16x32_bf16 v[94:97], v[146:149], v[208:211], v[94:97]
	v_mfma_f32_16x16x32_bf16 v[86:89], v[154:157], v[208:211], v[86:89]
	v_mfma_f32_16x16x32_bf16 v[78:81], v[146:149], v[216:219], v[78:81]
	v_mfma_f32_16x16x32_bf16 v[70:73], v[154:157], v[216:219], v[70:73]
	v_mfma_f32_16x16x32_bf16 v[126:129], v[150:153], v[188:191], v[126:129]
	v_mfma_f32_16x16x32_bf16 v[118:121], v[158:161], v[188:191], v[118:121]
	v_mfma_f32_16x16x32_bf16 v[110:113], v[150:153], v[196:199], v[110:113]
	v_mfma_f32_16x16x32_bf16 v[102:105], v[158:161], v[196:199], v[102:105]
	v_mfma_f32_16x16x32_bf16 v[94:97], v[150:153], v[212:215], v[94:97]
	v_mfma_f32_16x16x32_bf16 v[86:89], v[158:161], v[212:215], v[86:89]
	v_mfma_f32_16x16x32_bf16 v[78:81], v[150:153], v[220:223], v[78:81]
	v_mfma_f32_16x16x32_bf16 v[70:73], v[158:161], v[220:223], v[70:73]
	s_setprio 0
	s_setprio 1
	v_mfma_f32_16x16x32_bf16 v[122:125], v[162:165], v[184:187], v[122:125]
	v_mfma_f32_16x16x32_bf16 v[114:117], v[176:179], v[184:187], v[114:117]
	v_mfma_f32_16x16x32_bf16 v[106:109], v[162:165], v[192:195], v[106:109]
	v_mfma_f32_16x16x32_bf16 v[98:101], v[176:179], v[192:195], v[98:101]
	v_mfma_f32_16x16x32_bf16 v[90:93], v[162:165], v[208:211], v[90:93]
	v_mfma_f32_16x16x32_bf16 v[82:85], v[176:179], v[208:211], v[82:85]
	v_mfma_f32_16x16x32_bf16 v[74:77], v[162:165], v[216:219], v[74:77]
	v_mfma_f32_16x16x32_bf16 v[66:69], v[176:179], v[216:219], v[66:69]
	v_mfma_f32_16x16x32_bf16 v[122:125], v[166:169], v[188:191], v[122:125]
	v_mfma_f32_16x16x32_bf16 v[114:117], v[180:183], v[188:191], v[114:117]
	v_mfma_f32_16x16x32_bf16 v[106:109], v[166:169], v[196:199], v[106:109]
	v_mfma_f32_16x16x32_bf16 v[98:101], v[180:183], v[196:199], v[98:101]
	v_mfma_f32_16x16x32_bf16 v[90:93], v[166:169], v[212:215], v[90:93]
	v_mfma_f32_16x16x32_bf16 v[82:85], v[180:183], v[212:215], v[82:85]
	v_mfma_f32_16x16x32_bf16 v[74:77], v[166:169], v[220:223], v[74:77]
	v_mfma_f32_16x16x32_bf16 v[66:69], v[180:183], v[220:223], v[66:69]
	s_setprio 0
	s_barrier
; #define PG8_STAGE(bufoff, gbase, voff) do { _Pragma("unroll") for (int _i = 0; _i < 2; ++_i) \
;         __builtin_amdgcn_global_load_lds((const unsigned*)((const char*)(gbase) + (voff)[_i]), (PG8_LAS unsigned*)(lds + (bufoff) + ldsw + _i * 8192), 16, 0, 0); } while (0)
; #define PG8_LDA(dst, b, h) do { _Pragma("unroll") for (int m = 0; m < 4; ++m) _Pragma("unroll") for (int k = 0; k < 2; ++k) dst[m][k] = *(const PG8_LAS bf16x8*)(lds + PG8_SA(b, h) + aoff + m * 2048 + k * 1024); } while (0)
; #define PG8_WAIT_V(n) asm volatile("s_waitcnt vmcnt(" #n ")" ::: "memory")
; #define PG8_BAR __builtin_amdgcn_s_barrier()
; template <class Epi, class Sched, bool ALIGN_EPI = false, bool SP2 = false>
; __device__ __forceinline__ void gemm_phase(PG8_LAS unsigned char* lds, const Gemm g, const Sched& S, const Epi& E, int wave_s) {
;     ...
;         for (int t = 0; t < nt; t += 2) {
;             const bool last = (t == nt - 2);
;             const char* a1 = cA + (size_t)(t + 1) * kstep;
;             const char* a2 = last ? nA : cA + (size_t)(t + 2) * kstep; const char* b2 = last ? nB : cB + (size_t)(t + 2) * kstep;
;             const char* a3 = a2 + kstep; const char* b3 = b2 + kstep;
;             if (last && has_next) S.a_ready(nxt);
;             if constexpr (Epi::HAS_MID) { if (t == nt / 2) E.mid(acc, cur, wr, wc, fr, fq); }
;             if constexpr (SP2) {
;             PG8_LDB(B0, 0, 0); PG8_LDB(B1, 0, 1); PG8_SCHED; PG8_LDA(At, 0, 0); PG8_STAGE(PG8_SA(1, 1), a1 + hstepA, voffA);
;             PG8_WAIT_V(8); PG8_WAIT_L(0); PG8_BAR; PG8_MMA(0, 0, At, B0); PG8_MMA(0, 1, At, B1); PG8_BAR; PG8_SCHED;
;             PG8_LDA(At, 0, 1); PG8_STAGE(PG8_SB(0, 0), b2, voffB); PG8_STAGE(PG8_SB(0, 1), b2 + hstepB, voffB); PG8_STAGE(PG8_SA(0, 0), a2, voffA);
;             PG8_WAIT_V(8); PG8_WAIT_L(0); PG8_BAR; PG8_MMA(1, 0, At, B0); PG8_MMA(1, 1, At, B1); PG8_BAR; PG8_SCHED;
;             PG8_LDB(B0, 1, 0); PG8_LDB(B1, 1, 1); PG8_SCHED; PG8_LDA(At, 1, 0); PG8_STAGE(PG8_SA(0, 1), a2 + hstepA, voffA);
;             PG8_WAIT_V(8); PG8_WAIT_L(0); PG8_BAR; PG8_MMA(0, 0, At, B0); PG8_MMA(0, 1, At, B1); PG8_BAR; PG8_SCHED;
;             PG8_LDA(At, 1, 1); PG8_STAGE(PG8_SB(1, 0), b3, voffB); PG8_STAGE(PG8_SB(1, 1), b3 + hstepB, voffB); PG8_STAGE(PG8_SA(1, 0), a3, voffA);
;             PG8_WAIT_V(8); PG8_WAIT_L(0); PG8_BAR; PG8_MMA(1, 0, At, B0); PG8_MMA(1, 1, At, B1); PG8_BAR; PG8_SCHED;
	s_add_i32 s24, s34, s40
	s_mov_b64 s[100:101], 0x8000
	v_lshl_add_u64 v[140:141], v[140:141], 0, s[100:101]
	s_mov_b32 m0, s24
	ds_read_b128 v[184:187], v145 offset:49152
	ds_read_b128 v[188:191], v145 offset:50176
	ds_read_b128 v[192:195], v145 offset:51200
	ds_read_b128 v[196:199], v145 offset:52224
	ds_read_b128 v[208:211], v145 offset:53248
	ds_read_b128 v[212:215], v145 offset:54272
	ds_read_b128 v[216:219], v145 offset:55296
	ds_read_b128 v[220:223], v145 offset:56320
	global_load_lds_dwordx4 v[140:141], off
	s_add_i32 m0, s24, 0x2000
	s_add_u32 s20, s20, 0xc000
	v_lshl_add_u64 v[140:141], v[170:171], 0, s[100:101]
	s_addc_u32 s21, s21, 0
	s_add_i32 s24, s35, s40
	global_load_lds_dwordx4 v[140:141], off
	v_lshl_add_u64 v[140:141], s[20:21], 0, v[0:1]
	s_mov_b32 m0, s24
	s_nop 0
	global_load_lds_dwordx4 v[140:141], off
	v_lshl_add_u64 v[140:141], s[20:21], 0, v[130:131]
	s_add_i32 m0, s24, 0x2000
	s_nop 0
	global_load_lds_dwordx4 v[140:141], off
	v_lshl_add_u64 v[140:141], v[200:201], 0, s[30:31]
	s_mov_b32 m0, s45
	s_nop 0
	global_load_lds_dwordx4 v[140:141], off
	v_lshl_add_u64 v[140:141], v[224:225], 0, s[30:31]
	s_mov_b32 m0, s46
	s_nop 0
	global_load_lds_dwordx4 v[140:141], off
	s_waitcnt vmcnt(8)
	s_waitcnt lgkmcnt(0)
	s_barrier
	s_setprio 1
	s_waitcnt lgkmcnt(0)
	v_mfma_f32_16x16x32_bf16 v[62:65], v[146:149], v[184:187], v[62:65]
	v_mfma_f32_16x16x32_bf16 v[54:57], v[154:157], v[184:187], v[54:57]
	v_mfma_f32_16x16x32_bf16 v[46:49], v[146:149], v[192:195], v[46:49]
	v_mfma_f32_16x16x32_bf16 v[38:41], v[154:157], v[192:195], v[38:41]
	v_mfma_f32_16x16x32_bf16 v[30:33], v[146:149], v[208:211], v[30:33]
	v_mfma_f32_16x16x32_bf16 v[22:25], v[154:157], v[208:211], v[22:25]
	v_mfma_f32_16x16x32_bf16 v[14:17], v[146:149], v[216:219], v[14:17]
	v_mfma_f32_16x16x32_bf16 v[6:9], v[154:157], v[216:219], v[6:9]
	v_mfma_f32_16x16x32_bf16 v[62:65], v[150:153], v[188:191], v[62:65]
	v_mfma_f32_16x16x32_bf16 v[54:57], v[158:161], v[188:191], v[54:57]
	v_mfma_f32_16x16x32_bf16 v[46:49], v[150:153], v[196:199], v[46:49]
	v_mfma_f32_16x16x32_bf16 v[38:41], v[158:161], v[196:199], v[38:41]
	v_mfma_f32_16x16x32_bf16 v[30:33], v[150:153], v[212:215], v[30:33]
	v_mfma_f32_16x16x32_bf16 v[22:25], v[158:161], v[212:215], v[22:25]
	v_mfma_f32_16x16x32_bf16 v[14:17], v[150:153], v[220:223], v[14:17]
	v_mfma_f32_16x16x32_bf16 v[6:9], v[158:161], v[220:223], v[6:9]
	s_setprio 0
	s_setprio 1
	v_mfma_f32_16x16x32_bf16 v[58:61], v[162:165], v[184:187], v[58:61]
	v_mfma_f32_16x16x32_bf16 v[50:53], v[176:179], v[184:187], v[50:53]
	v_mfma_f32_16x16x32_bf16 v[42:45], v[162:165], v[192:195], v[42:45]
	v_mfma_f32_16x16x32_bf16 v[34:37], v[176:179], v[192:195], v[34:37]
	v_mfma_f32_16x16x32_bf16 v[26:29], v[162:165], v[208:211], v[26:29]
	v_mfma_f32_16x16x32_bf16 v[18:21], v[176:179], v[208:211], v[18:21]
	v_mfma_f32_16x16x32_bf16 v[10:13], v[162:165], v[216:219], v[10:13]
	v_mfma_f32_16x16x32_bf16 v[2:5], v[176:179], v[216:219], v[2:5]
	v_mfma_f32_16x16x32_bf16 v[58:61], v[166:169], v[188:191], v[58:61]
	v_mfma_f32_16x16x32_bf16 v[50:53], v[180:183], v[188:191], v[50:53]
	v_mfma_f32_16x16x32_bf16 v[42:45], v[166:169], v[196:199], v[42:45]
	v_mfma_f32_16x16x32_bf16 v[34:37], v[180:183], v[196:199], v[34:37]
	v_mfma_f32_16x16x32_bf16 v[26:29], v[166:169], v[212:215], v[26:29]
	v_mfma_f32_16x16x32_bf16 v[18:21], v[180:183], v[212:215], v[18:21]
	v_mfma_f32_16x16x32_bf16 v[10:13], v[166:169], v[220:223], v[10:13]
	v_mfma_f32_16x16x32_bf16 v[2:5], v[180:183], v[220:223], v[2:5]
	s_setprio 0
	s_barrier
	s_add_i32 s51, s51, 2
	s_add_u32 s49, s49, 0x10000
	s_addc_u32 s50, s50, 0
	s_add_u32 s18, s18, 0x100
	s_addc_u32 s19, s19, 0
	s_cmp_gt_u32 s51, 29
	s_cbranch_scc0 .LBB0_279
	s_and_b64 vcc, exec, s[8:9]
	s_cbranch_vccz .LBB0_282
	s_barrier

; template <class Epi, class Sched, bool ALIGN_EPI = false, bool SP2 = false>
; __device__ __forceinline__ void gemm_phase(PG8_LAS unsigned char* lds, const Gemm g, const Sched& S, const Epi& E, int wave_s) {
;     int tid_ = (wave_s << 6) | fresh_lane(); asm volatile("" : "+v"(tid_));
;     const int tid = tid_, wid = __builtin_amdgcn_readfirstlane(tid >> 6), lane = tid & 63, wr = wid >> 2, wc = wid & 3, fr = lane & 15, fq = lane >> 4;
;     const int K = g.K, nt = K / BK;
;     unsigned voffA[2], voffB[2];
; #pragma unroll
;     for (int i = 0; i < 2; ++i) { int R, C; stage_rc(tid * 16 + i * 8192, R, C); const int Rb = Epi::PERM ? ((R & ~31) + perm32(R & 31)) : R;
;         voffA[i] = (unsigned)(R * g.lda + C) * 2u; voffB[i] = (unsigned)(Rb * g.ldb + C) * 2u; }
;     const size_t kstep = (size_t)(BK * 2);
;     const size_t hstepA = (size_t)HALF * g.lda * 2, hstepB = (size_t)HALF * g.ldb * 2;
;     const size_t tstepA = 2 * hstepA, tstepB = 2 * hstepB;
;     const unsigned ldsw = (unsigned)wid * 1024u;
;     const int aoff = lds_byte(wr * 64 + fr, fq * 8), boff = lds_byte(wc * 32 + fr, fq * 8);
;     ...
;     Unit cur, nxt; int ui = 0;
;     if (!S.next(0, cur)) return;
;     f32x4 acc[2][2][4][2];
; #pragma unroll
;     for (int a = 0; a < 2; ++a)
; #pragma unroll
;         for (int b = 0; b < 2; ++b)
; #pragma unroll
;             for (int m = 0; m < 4; ++m)
; #pragma unroll
;                 for (int n = 0; n < 2; ++n) acc[a][b][m][n] = (f32x4){0.f, 0.f, 0.f, 0.f};
;     bf16x8 At[4][2], B0[2][2], B1[2][2];
;     const char* cA = (const char*)g.A + (size_t)cur.pm * tstepA; const char* cB = (const char*)g.Bt + (size_t)cur.pn * tstepB;
;     S.a_ready(cur);
;     if constexpr (SP2) {
;         PG8_STAGE(PG8_SB(0, 0), cB, voffB); PG8_STAGE(PG8_SB(0, 1), cB + hstepB, voffB); PG8_STAGE(PG8_SA(0, 0), cA, voffA); PG8_STAGE(PG8_SA(0, 1), cA + hstepA, voffA);
;         if (wr == 1) PG8_BAR;
;         PG8_WAIT_V(2); PG8_BAR;
;         PG8_STAGE(PG8_SB(1, 0), cB + kstep, voffB); PG8_STAGE(PG8_SA(1, 0), cA + kstep, voffA); PG8_STAGE(PG8_SB(1, 1), cB + hstepB + kstep, voffB);
;         PG8_WAIT_V(6); PG8_BAR;
;     } else {
;         PG8_STAGE(PG8_SB(0, 0), cB, voffB); PG8_STAGE(PG8_SA(0, 0), cA, voffA); PG8_STAGE(PG8_SB(0, 1), cB + hstepB, voffB); PG8_STAGE(PG8_SA(0, 1), cA + hstepA, voffA);
;         if (wr == 1) PG8_BAR;
;         PG8_WAIT_V(4); PG8_BAR;
.LBB0_1787:
	s_andn2_b64 vcc, exec, s[0:1]
	s_cbranch_vccnz .LBB0_1852
	s_load_dwordx2 s[6:7], s[82:83], 0xb8
	v_mov_b32_e32 v0, v1
	s_waitcnt lgkmcnt(0)
	v_readlane_b32 s0, v253, 21
	v_mbcnt_lo_u32_b32 v0, -1, v0
	v_mbcnt_hi_u32_b32 v0, -1, v0
	v_or_b32_e32 v0, s0, v0
	s_nop 0
	v_readfirstlane_b32 s0, v0
	v_mov_b32_e32 v0, v1
	s_andn2_b32 s0, s0, 63
	v_mbcnt_lo_u32_b32 v0, -1, v0
	v_mbcnt_hi_u32_b32 v0, -1, v0
	v_or_b32_e32 v16, s0, v0
	v_readlane_b32 s0, v255, 49
	v_readlane_b32 s1, v255, 50
	s_and_b64 vcc, exec, s[0:1]
	v_readfirstlane_b32 s8, v16
	s_cbranch_vccnz .LBB0_1804
	v_lshlrev_b32_e32 v0, 4, v16
	v_add_u32_e32 v2, 0x2000, v0
	v_ashrrev_i32_e32 v3, 31, v2
	v_lshrrev_b32_e32 v3, 22, v3
	v_add_u32_e32 v3, v2, v3
	v_ashrrev_i32_e32 v10, 10, v3
	v_mul_i32_i24_e32 v3, 0x400, v10
	v_sub_u32_e32 v2, v2, v3
	v_lshrrev_b32_e32 v3, 4, v2
	v_bitop3_b32 v2, v3, v2, 32 bitop3:0x6c
	v_ashrrev_i32_e32 v3, 31, v2
	s_add_u32 s2, s6, 0x1ed90000
	v_lshrrev_b32_e32 v3, 26, v3
	s_addc_u32 s22, s7, 0
	s_mul_i32 s0, s78, 0x5800000
	v_add_u32_e32 v3, v2, v3
	v_lshlrev_b32_e32 v4, 3, v10
	s_add_u32 s0, s6, s0
	v_ashrrev_i32_e32 v11, 6, v3
	v_and_b32_e32 v4, -16, v4
	s_addc_u32 s1, s7, 0
	v_add_u32_e32 v4, v11, v4
	s_add_u32 s40, s0, 0x2d90000
	v_and_b32_e32 v5, 3, v11
	s_mov_b32 s0, 0xfffe0
	v_lshrrev_b32_e32 v6, 2, v4
	v_lshlrev_b32_e32 v7, 1, v4
	v_and_or_b32 v5, v4, s0, v5
	v_and_b32_e32 v6, 4, v6
	v_and_b32_e32 v7, 24, v7
	v_and_b32_e32 v3, 0xc0, v3
	v_or3_b32 v5, v5, v6, v7
	v_sub_u32_e32 v2, v2, v3
	v_mov_b32_e32 v7, 1
	v_lshlrev_b32_e32 v6, 5, v10
	v_ashrrev_i16_sdwa v2, v7, sext(v2) dst_sel:DWORD dst_unused:UNUSED_PAD src0_sel:DWORD src1_sel:BYTE_0
	v_and_b32_e32 v6, 32, v6
	v_bfe_i32 v12, v2, 0, 16
	v_add_lshl_u32 v2, v6, v12, 1
	s_waitcnt vmcnt(0)
	v_lshl_add_u32 v130, v5, 7, v2
	v_lshl_add_u32 v132, v4, 12, v2
	v_bfe_i32 v2, v16, 27, 1
	v_lshrrev_b32_e32 v2, 22, v2
	v_add_u32_e32 v2, v0, v2
	v_and_b32_e32 v2, 0xfffffc00, v2
	v_sub_u32_e32 v0, v0, v2
	v_lshrrev_b32_e32 v2, 4, v0
	v_ashrrev_i32_e32 v3, 31, v16
	v_bitop3_b32 v0, v2, v0, 32 bitop3:0x6c
	v_lshrrev_b32_e32 v3, 26, v3
	v_ashrrev_i32_e32 v2, 31, v0
	v_add_u32_e32 v3, v16, v3
	v_lshrrev_b32_e32 v2, 26, v2
	v_ashrrev_i32_e32 v14, 6, v3
	v_add_u32_e32 v2, v0, v2
	v_lshlrev_b32_e32 v3, 3, v14
	v_ashrrev_i32_e32 v13, 6, v2
	v_and_b32_e32 v3, -16, v3
	v_add_u32_e32 v3, v13, v3
	v_and_b32_e32 v4, 3, v13
	v_lshrrev_b32_e32 v5, 2, v3
	v_lshlrev_b32_e32 v6, 1, v3
	v_and_b32_e32 v2, 0xc0, v2
	s_addc_u32 s41, s1, 0
	s_ashr_i32 s9, s8, 6
	v_and_or_b32 v4, v3, s0, v4
	v_and_b32_e32 v5, 4, v5
	v_and_b32_e32 v6, 24, v6
	v_sub_u32_e32 v0, v0, v2
	s_ashr_i32 s10, s8, 8
	s_lshl_b32 s42, s9, 10
	v_or3_b32 v4, v4, v5, v6
	v_lshlrev_b32_e32 v5, 5, v14
	v_ashrrev_i16_sdwa v0, v7, sext(v0) dst_sel:DWORD dst_unused:UNUSED_PAD src0_sel:DWORD src1_sel:BYTE_0
	v_readlane_b32 s0, v254, 47
	v_and_b32_e32 v5, 32, v5
	v_bfe_i32 v15, v0, 0, 16
	v_readlane_b32 s1, v254, 48
	s_add_u32 s18, s40, s0
	v_add_lshl_u32 v2, v5, v15, 1
	s_addc_u32 s19, s41, s1
	s_add_i32 s43, s42, 0
	v_lshl_add_u32 v0, v4, 7, v2
	s_add_i32 m0, s43, 0x10000
	v_lshl_add_u32 v134, v3, 12, v2
	global_load_lds_dwordx4 v0, s[18:19]
	s_add_i32 m0, s43, 0x12000
	s_add_u32 s0, s18, 0x4000
	global_load_lds_dwordx4 v130, s[18:19]
	s_addc_u32 s1, s19, 0
	s_add_i32 m0, s43, 0x14000
	v_mov_b32_e32 v131, v1
	global_load_lds_dwordx4 v0, s[0:1]
	s_add_i32 m0, s43, 0x16000
	v_mov_b32_e32 v135, v1
	global_load_lds_dwordx4 v130, s[0:1]
	v_readlane_b32 s0, v254, 56
	v_readlane_b32 s1, v254, 57
	s_add_u32 s20, s2, s0
	s_addc_u32 s21, s22, s1
	s_add_i32 s44, s43, 0x2000
	s_mov_b32 m0, s43
	s_add_u32 s0, s20, 0x80000
	global_load_lds_dwordx4 v134, s[20:21]
	s_mov_b32 m0, s44
	s_addc_u32 s1, s21, 0
	s_add_i32 s45, s43, 0x4000
	global_load_lds_dwordx4 v132, s[20:21]
	s_mov_b32 m0, s45
	s_add_i32 s46, s43, 0x6000
	global_load_lds_dwordx4 v134, s[0:1]
	s_mov_b32 m0, s46
	v_mov_b32_e32 v133, v1
	global_load_lds_dwordx4 v132, s[0:1]
	s_cmp_eq_u32 s10, 1
	v_lshl_add_u64 v[8:9], s[18:19], 0, v[0:1]
	v_lshl_add_u64 v[6:7], s[18:19], 0, v[130:131]
	v_lshl_add_u64 v[2:3], s[20:21], 0, v[134:135]
	s_cselect_b64 s[0:1], -1, 0
	s_cmp_lg_u32 s10, 1
	v_lshl_add_u64 v[4:5], s[20:21], 0, v[132:133]
	s_cbranch_scc1 .LBB0_1791
	s_barrier
.LBB0_1791:
	s_add_u32 s6, s6, 0x22d90000
	v_lshrrev_b32_e32 v18, 1, v16
	s_addc_u32 s7, s7, 0
	v_and_b32_e32 v18, 24, v18
	s_lshl_b32 s9, s9, 5
	v_and_b32_e32 v17, 15, v16
	v_lshlrev_b32_e32 v19, 1, v18
	v_lshlrev_b32_e32 v16, 2, v16
	s_and_b32 s12, s9, 0x60
	s_add_i32 m0, s43, 0x18000
	s_mov_b64 s[100:101], 0x8000
	v_lshl_add_u64 v[8:9], v[8:9], 0, s[100:101]
	v_lshl_or_b32 v142, s10, 6, v17
	v_lshl_or_b32 v17, v17, 6, v19
	s_lshl_b32 s10, s10, 13
	v_and_b32_e32 v16, 32, v16
	s_lshl_b32 s9, s12, 7
	s_waitcnt vmcnt(2)
	s_barrier
	global_load_lds_dwordx4 v[8:9], off
	v_lshl_add_u64 v[6:7], v[6:7], 0, s[100:101]
	s_add_i32 m0, s43, 0x1a000
	s_add_i32 s47, s43, 0x8000
	s_add_i32 s48, s43, 0xa000
	v_bitop3_b32 v19, v17, s10, v16 bitop3:0xde
	global_load_lds_dwordx4 v[6:7], off
	v_lshl_add_u64 v[2:3], v[2:3], 0, s[30:31]
	s_mov_b32 m0, s47
	s_add_u32 s10, s18, 0xc000
	global_load_lds_dwordx4 v[2:3], off
	v_lshl_add_u64 v[2:3], v[4:5], 0, s[30:31]
	s_mov_b32 m0, s48
	s_addc_u32 s11, s19, 0
	global_load_lds_dwordx4 v[2:3], off
	s_add_i32 m0, s43, 0x1c000
	v_lshl_add_u64 v[2:3], s[10:11], 0, v[0:1]
	global_load_lds_dwordx4 v[2:3], off
	v_lshl_add_u64 v[2:3], s[10:11], 0, v[130:131]
	s_add_i32 m0, s43, 0x1e000
	s_cmpk_lt_u32 s8, 0x100
	global_load_lds_dwordx4 v[2:3], off
	v_lshlrev_b32_e32 v2, 15, v10
	v_and_b32_e32 v2, 0xffff0000, v2
	v_lshl_add_u32 v2, v11, 12, v2
	v_and_b32_e32 v3, 1, v10
	v_lshl_or_b32 v2, v3, 6, v2
	v_lshl_add_u32 v136, v12, 1, v2
	v_lshlrev_b32_e32 v2, 15, v14
	v_and_b32_e32 v2, 0xffff0000, v2
	s_waitcnt vmcnt(6)
	v_lshl_add_u32 v2, v13, 12, v2
	v_and_b32_e32 v3, 1, v14
	v_lshl_or_b32 v2, v3, 6, v2
	v_readlane_b32 s10, v254, 54
	v_bitop3_b32 v143, v17, s9, v16 bitop3:0xde
	s_cselect_b64 s[8:9], -1, 0
	v_or_b32_e32 v144, s12, v18
	v_mov_b32_e32 v137, v1
	v_lshl_add_u32 v138, v15, 1, v2
	v_mov_b32_e32 v139, v1
	s_mov_b32 s49, 0
	v_add_u32_e32 v145, 0, v19
	v_readlane_b32 s26, v254, 46
	s_mov_b32 s27, s10
	s_barrier
	v_readlane_b32 s11, v254, 55
	s_branch .LBB0_1794

; #define PG8_STAGE(bufoff, gbase, voff) do { _Pragma("unroll") for (int _i = 0; _i < 2; ++_i) \
;         __builtin_amdgcn_global_load_lds((const unsigned*)((const char*)(gbase) + (voff)[_i]), (PG8_LAS unsigned*)(lds + (bufoff) + ldsw + _i * 8192), 16, 0, 0); } while (0)
; #define PG8_LDA(dst, b, h) do { _Pragma("unroll") for (int m = 0; m < 4; ++m) _Pragma("unroll") for (int k = 0; k < 2; ++k) dst[m][k] = *(const PG8_LAS bf16x8*)(lds + PG8_SA(b, h) + aoff + m * 2048 + k * 1024); } while (0)
; #define PG8_LDB(dst, b, h) do { _Pragma("unroll") for (int n = 0; n < 2; ++n) _Pragma("unroll") for (int k = 0; k < 2; ++k) dst[n][k] = *(const PG8_LAS bf16x8*)(lds + PG8_SB(b, h) + boff + n * 2048 + k * 1024); } while (0)
; #define PG8_MMA(ai, bj, At, Bt) do { __builtin_amdgcn_s_setprio(1); _Pragma("unroll") for (int m = 0; m < 4; ++m) _Pragma("unroll") for (int n = 0; n < 2; ++n) _Pragma("unroll") for (int k = 0; k < 2; ++k) \
;         acc[ai][bj][m][n] = __builtin_amdgcn_mfma_f32_16x16x32_bf16(Bt[n][k], At[m][k], acc[ai][bj][m][n], 0, 0, 0); __builtin_amdgcn_s_setprio(0); } while (0)
; #define PG8_WAIT_V(n) asm volatile("s_waitcnt vmcnt(" #n ")" ::: "memory")
; template <class Epi, class Sched, bool ALIGN_EPI = false, bool SP2 = false>
; __device__ __forceinline__ void gemm_phase(PG8_LAS unsigned char* lds, const Gemm g, const Sched& S, const Epi& E, int wave_s) {
;     ...
;         const bool has_next = S.next(ui + 1, nxt);
;         const char* nA = has_next ? (const char*)g.A + (size_t)nxt.pm * tstepA : cA; const char* nB = has_next ? (const char*)g.Bt + (size_t)nxt.pn * tstepB : cB;
;         for (int t = 0; t < nt; t += 2) {
;             const bool last = (t == nt - 2);
;             const char* a1 = cA + (size_t)(t + 1) * kstep;
;             const char* a2 = last ? nA : cA + (size_t)(t + 2) * kstep; const char* b2 = last ? nB : cB + (size_t)(t + 2) * kstep;
;             const char* a3 = a2 + kstep; const char* b3 = b2 + kstep;
;             if (last && has_next) S.a_ready(nxt);
;             if constexpr (Epi::HAS_MID) { if (t == nt / 2) E.mid(acc, cur, wr, wc, fr, fq); }
;             if constexpr (SP2) {
;             PG8_LDB(B0, 0, 0); PG8_LDB(B1, 0, 1); PG8_SCHED; PG8_LDA(At, 0, 0); PG8_STAGE(PG8_SA(1, 1), a1 + hstepA, voffA);
;             PG8_WAIT_V(8); PG8_WAIT_L(0); PG8_BAR; PG8_MMA(0, 0, At, B0); PG8_MMA(0, 1, At, B1); PG8_BAR; PG8_SCHED;
.LBB0_1796:
	s_ashr_i32 s13, s12, 31
	s_lshl_b64 s[14:15], s[12:13], 20
	s_add_u32 s14, s2, s14
	s_addc_u32 s15, s22, s15
	s_and_b64 s[16:17], s[36:37], exec
	s_cselect_b32 s13, s15, s21
	s_cselect_b32 s33, s14, s20
	s_ashr_i32 s11, s10, 31
	s_lshl_b64 s[16:17], s[10:11], 20
	s_add_u32 s16, s40, s16
	s_addc_u32 s17, s41, s17
	s_and_b64 s[24:25], s[36:37], exec
	s_cselect_b32 s11, s17, s19
	s_cselect_b32 s50, s16, s18
	s_add_u32 s51, s18, 0x10000
	s_addc_u32 s54, s19, 0
	s_add_u32 s18, s20, 0x80080
	v_mov_b32_e32 v2, 0
	s_addc_u32 s19, s21, 0
	s_mov_b32 s55, -2
	v_mov_b32_e32 v3, v2
	v_mov_b32_e32 v4, v2
	v_mov_b32_e32 v5, v2
	v_mov_b32_e32 v10, v2
	v_mov_b32_e32 v11, v2
	v_mov_b32_e32 v12, v2
	v_mov_b32_e32 v13, v2
	v_mov_b32_e32 v18, v2
	v_mov_b32_e32 v19, v2
	v_mov_b32_e32 v20, v2
	v_mov_b32_e32 v21, v2
	v_mov_b32_e32 v26, v2
	v_mov_b32_e32 v27, v2
	v_mov_b32_e32 v28, v2
	v_mov_b32_e32 v29, v2
	v_mov_b32_e32 v34, v2
	v_mov_b32_e32 v35, v2
	v_mov_b32_e32 v36, v2
	v_mov_b32_e32 v37, v2
	v_mov_b32_e32 v42, v2
	v_mov_b32_e32 v43, v2
	v_mov_b32_e32 v44, v2
	v_mov_b32_e32 v45, v2
	v_mov_b32_e32 v50, v2
	v_mov_b32_e32 v51, v2
	v_mov_b32_e32 v52, v2
	v_mov_b32_e32 v53, v2
	v_mov_b32_e32 v58, v2
	v_mov_b32_e32 v59, v2
	v_mov_b32_e32 v60, v2
	v_mov_b32_e32 v61, v2
	v_mov_b32_e32 v6, v2
	v_mov_b32_e32 v7, v2
	v_mov_b32_e32 v8, v2
	v_mov_b32_e32 v9, v2
	v_mov_b32_e32 v14, v2
	v_mov_b32_e32 v15, v2
	v_mov_b32_e32 v16, v2
	v_mov_b32_e32 v17, v2
	v_mov_b32_e32 v22, v2
	v_mov_b32_e32 v23, v2
	v_mov_b32_e32 v24, v2
	v_mov_b32_e32 v25, v2
	v_mov_b32_e32 v30, v2
	v_mov_b32_e32 v31, v2
	v_mov_b32_e32 v32, v2
	v_mov_b32_e32 v33, v2
	v_mov_b32_e32 v38, v2
	v_mov_b32_e32 v39, v2
	v_mov_b32_e32 v40, v2
	v_mov_b32_e32 v41, v2
	v_mov_b32_e32 v46, v2
	v_mov_b32_e32 v47, v2
	v_mov_b32_e32 v48, v2
	v_mov_b32_e32 v49, v2
	v_mov_b32_e32 v54, v2
	v_mov_b32_e32 v55, v2
	v_mov_b32_e32 v56, v2
	v_mov_b32_e32 v57, v2
	v_mov_b32_e32 v62, v2
	v_mov_b32_e32 v63, v2
	v_mov_b32_e32 v64, v2
	v_mov_b32_e32 v65, v2
	v_mov_b32_e32 v66, v2
	v_mov_b32_e32 v67, v2
	v_mov_b32_e32 v68, v2
	v_mov_b32_e32 v69, v2
	v_mov_b32_e32 v74, v2
	v_mov_b32_e32 v75, v2
	v_mov_b32_e32 v76, v2
	v_mov_b32_e32 v77, v2
	v_mov_b32_e32 v82, v2
	v_mov_b32_e32 v83, v2
	v_mov_b32_e32 v84, v2
	v_mov_b32_e32 v85, v2
	v_mov_b32_e32 v90, v2
	v_mov_b32_e32 v91, v2
	v_mov_b32_e32 v92, v2
	v_mov_b32_e32 v93, v2
	v_mov_b32_e32 v98, v2
	v_mov_b32_e32 v99, v2
	v_mov_b32_e32 v100, v2
	v_mov_b32_e32 v101, v2
	v_mov_b32_e32 v106, v2
	v_mov_b32_e32 v107, v2
	v_mov_b32_e32 v108, v2
	v_mov_b32_e32 v109, v2
	v_mov_b32_e32 v114, v2
	v_mov_b32_e32 v115, v2
	v_mov_b32_e32 v116, v2
	v_mov_b32_e32 v117, v2
	v_mov_b32_e32 v122, v2
	v_mov_b32_e32 v123, v2
	v_mov_b32_e32 v124, v2
	v_mov_b32_e32 v125, v2
	v_mov_b32_e32 v70, v2
	v_mov_b32_e32 v71, v2
	v_mov_b32_e32 v72, v2
	v_mov_b32_e32 v73, v2
	v_mov_b32_e32 v78, v2
	v_mov_b32_e32 v79, v2
	v_mov_b32_e32 v80, v2
	v_mov_b32_e32 v81, v2
	v_mov_b32_e32 v86, v2
	v_mov_b32_e32 v87, v2
	v_mov_b32_e32 v88, v2
	v_mov_b32_e32 v89, v2
	v_mov_b32_e32 v94, v2
	v_mov_b32_e32 v95, v2
	v_mov_b32_e32 v96, v2
	v_mov_b32_e32 v97, v2
	v_mov_b32_e32 v102, v2
	v_mov_b32_e32 v103, v2
	v_mov_b32_e32 v104, v2
	v_mov_b32_e32 v105, v2
	v_mov_b32_e32 v110, v2
	v_mov_b32_e32 v111, v2
	v_mov_b32_e32 v112, v2
	v_mov_b32_e32 v113, v2
	v_mov_b32_e32 v118, v2
	v_mov_b32_e32 v119, v2
	v_mov_b32_e32 v120, v2
	v_mov_b32_e32 v121, v2
	v_mov_b32_e32 v126, v2
	v_mov_b32_e32 v127, v2
	v_mov_b32_e32 v128, v2
	v_mov_b32_e32 v129, v2
.LBB0_1797:
	s_add_u32 s20, s18, 0xfff80080
	s_addc_u32 s21, s19, -1
	s_add_i32 s34, 0, 0x10000
	s_cmp_eq_u32 s55, 28
	s_cselect_b32 s25, s13, s21
	s_cselect_b32 s24, s33, s20
	v_add_u32_e32 v140, s34, v143
	s_cselect_b32 s21, s11, s54
	s_cselect_b32 s20, s50, s51
	s_add_i32 s56, 0, 0x14000
	ds_read_b128 v[146:149], v140
	ds_read_b128 v[150:153], v140 offset:1024
	ds_read_b128 v[154:157], v140 offset:2048
	ds_read_b128 v[158:161], v140 offset:3072
	v_add_u32_e32 v140, s56, v143
	ds_read_b128 v[162:165], v140
	ds_read_b128 v[166:169], v140 offset:1024
	ds_read_b128 v[176:179], v140 offset:2048
	ds_read_b128 v[180:183], v140 offset:3072
	v_lshl_add_u64 v[140:141], s[18:19], 0, v[138:139]
	s_add_i32 m0, s43, 0xc000
	ds_read_b128 v[184:187], v145
	ds_read_b128 v[188:191], v145 offset:1024
	ds_read_b128 v[192:195], v145 offset:2048
	ds_read_b128 v[196:199], v145 offset:3072
	ds_read_b128 v[208:211], v145 offset:4096
	ds_read_b128 v[212:215], v145 offset:5120
	ds_read_b128 v[216:219], v145 offset:6144
	ds_read_b128 v[220:223], v145 offset:7168
	global_load_lds_dwordx4 v[140:141], off
	v_lshl_add_u64 v[140:141], s[18:19], 0, v[136:137]
	s_add_i32 m0, s43, 0xe000
	s_nop 0
	global_load_lds_dwordx4 v[140:141], off
	s_waitcnt vmcnt(8)
	s_waitcnt lgkmcnt(0)
	s_barrier
; #define PG8_STAGE(bufoff, gbase, voff) do { _Pragma("unroll") for (int _i = 0; _i < 2; ++_i) \
;         __builtin_amdgcn_global_load_lds((const unsigned*)((const char*)(gbase) + (voff)[_i]), (PG8_LAS unsigned*)(lds + (bufoff) + ldsw + _i * 8192), 16, 0, 0); } while (0)
; #define PG8_LDA(dst, b, h) do { _Pragma("unroll") for (int m = 0; m < 4; ++m) _Pragma("unroll") for (int k = 0; k < 2; ++k) dst[m][k] = *(const PG8_LAS bf16x8*)(lds + PG8_SA(b, h) + aoff + m * 2048 + k * 1024); } while (0)
; #define PG8_MMA(ai, bj, At, Bt) do { __builtin_amdgcn_s_setprio(1); _Pragma("unroll") for (int m = 0; m < 4; ++m) _Pragma("unroll") for (int n = 0; n < 2; ++n) _Pragma("unroll") for (int k = 0; k < 2; ++k) \
;         acc[ai][bj][m][n] = __builtin_amdgcn_mfma_f32_16x16x32_bf16(Bt[n][k], At[m][k], acc[ai][bj][m][n], 0, 0, 0); __builtin_amdgcn_s_setprio(0); } while (0)
; #define PG8_WAIT_V(n) asm volatile("s_waitcnt vmcnt(" #n ")" ::: "memory")
; #define PG8_WAIT_L(n) asm volatile("s_waitcnt lgkmcnt(" #n ")" ::: "memory")
; #define PG8_BAR __builtin_amdgcn_s_barrier()
; #define PG8_SCHED __builtin_amdgcn_sched_barrier(0)
; template <class Epi, class Sched, bool ALIGN_EPI = false, bool SP2 = false>
; __device__ __forceinline__ void gemm_phase(PG8_LAS unsigned char* lds, const Gemm g, const Sched& S, const Epi& E, int wave_s) {
;     ...
;             PG8_WAIT_V(8); PG8_WAIT_L(0); PG8_BAR; PG8_MMA(0, 0, At, B0); PG8_MMA(0, 1, At, B1); PG8_BAR; PG8_SCHED;
;             PG8_LDA(At, 0, 1); PG8_STAGE(PG8_SB(0, 0), b2, voffB); PG8_STAGE(PG8_SB(0, 1), b2 + hstepB, voffB); PG8_STAGE(PG8_SA(0, 0), a2, voffA);
;             PG8_WAIT_V(8); PG8_WAIT_L(0); PG8_BAR; PG8_MMA(1, 0, At, B0); PG8_MMA(1, 1, At, B1); PG8_BAR; PG8_SCHED;
	s_setprio 1
	s_waitcnt lgkmcnt(0)
	v_mfma_f32_16x16x32_bf16 v[126:129], v[146:149], v[184:187], v[126:129]
	v_mfma_f32_16x16x32_bf16 v[118:121], v[154:157], v[184:187], v[118:121]
	v_mfma_f32_16x16x32_bf16 v[110:113], v[146:149], v[192:195], v[110:113]
	v_mfma_f32_16x16x32_bf16 v[102:105], v[154:157], v[192:195], v[102:105]
	v_mfma_f32_16x16x32_bf16 v[94:97], v[146:149], v[208:211], v[94:97]
	v_mfma_f32_16x16x32_bf16 v[86:89], v[154:157], v[208:211], v[86:89]
	v_mfma_f32_16x16x32_bf16 v[78:81], v[146:149], v[216:219], v[78:81]
	v_mfma_f32_16x16x32_bf16 v[70:73], v[154:157], v[216:219], v[70:73]
	v_mfma_f32_16x16x32_bf16 v[126:129], v[150:153], v[188:191], v[126:129]
	v_mfma_f32_16x16x32_bf16 v[118:121], v[158:161], v[188:191], v[118:121]
	v_mfma_f32_16x16x32_bf16 v[110:113], v[150:153], v[196:199], v[110:113]
	v_mfma_f32_16x16x32_bf16 v[102:105], v[158:161], v[196:199], v[102:105]
	v_mfma_f32_16x16x32_bf16 v[94:97], v[150:153], v[212:215], v[94:97]
	v_mfma_f32_16x16x32_bf16 v[86:89], v[158:161], v[212:215], v[86:89]
	v_mfma_f32_16x16x32_bf16 v[78:81], v[150:153], v[220:223], v[78:81]
	v_mfma_f32_16x16x32_bf16 v[70:73], v[158:161], v[220:223], v[70:73]
	s_setprio 0
	s_setprio 1
	v_mfma_f32_16x16x32_bf16 v[122:125], v[162:165], v[184:187], v[122:125]
	v_mfma_f32_16x16x32_bf16 v[114:117], v[176:179], v[184:187], v[114:117]
	v_mfma_f32_16x16x32_bf16 v[106:109], v[162:165], v[192:195], v[106:109]
	v_mfma_f32_16x16x32_bf16 v[98:101], v[176:179], v[192:195], v[98:101]
	v_mfma_f32_16x16x32_bf16 v[90:93], v[162:165], v[208:211], v[90:93]
	v_mfma_f32_16x16x32_bf16 v[82:85], v[176:179], v[208:211], v[82:85]
	v_mfma_f32_16x16x32_bf16 v[74:77], v[162:165], v[216:219], v[74:77]
	v_mfma_f32_16x16x32_bf16 v[66:69], v[176:179], v[216:219], v[66:69]
	v_mfma_f32_16x16x32_bf16 v[122:125], v[166:169], v[188:191], v[122:125]
	v_mfma_f32_16x16x32_bf16 v[114:117], v[180:183], v[188:191], v[114:117]
	v_mfma_f32_16x16x32_bf16 v[106:109], v[166:169], v[196:199], v[106:109]
	v_mfma_f32_16x16x32_bf16 v[98:101], v[180:183], v[196:199], v[98:101]
	v_mfma_f32_16x16x32_bf16 v[90:93], v[166:169], v[212:215], v[90:93]
	v_mfma_f32_16x16x32_bf16 v[82:85], v[180:183], v[212:215], v[82:85]
	v_mfma_f32_16x16x32_bf16 v[74:77], v[166:169], v[220:223], v[74:77]
	v_mfma_f32_16x16x32_bf16 v[66:69], v[180:183], v[220:223], v[66:69]
	s_setprio 0
	s_barrier
	s_add_i32 s34, s34, s42
	v_lshl_add_u64 v[140:141], s[20:21], 0, v[0:1]
	s_mov_b32 m0, s34
	ds_read_b128 v[184:187], v145 offset:16384
	ds_read_b128 v[188:191], v145 offset:17408
	ds_read_b128 v[192:195], v145 offset:18432
	ds_read_b128 v[196:199], v145 offset:19456
	ds_read_b128 v[208:211], v145 offset:20480
	ds_read_b128 v[212:215], v145 offset:21504
	ds_read_b128 v[216:219], v145 offset:22528
	ds_read_b128 v[220:223], v145 offset:23552
	global_load_lds_dwordx4 v[140:141], off
	s_add_i32 m0, s34, 0x2000
	s_add_u32 s34, s20, 0x4000
	v_lshl_add_u64 v[170:171], s[20:21], 0, v[130:131]
	s_addc_u32 s35, s21, 0
	s_add_i32 s56, s56, s42
	global_load_lds_dwordx4 v[170:171], off
	v_lshl_add_u64 v[200:201], s[34:35], 0, v[0:1]
	s_mov_b32 m0, s56
	v_lshl_add_u64 v[224:225], s[24:25], 0, v[132:133]
	global_load_lds_dwordx4 v[200:201], off
	v_lshl_add_u64 v[200:201], s[34:35], 0, v[130:131]
	s_add_i32 m0, s56, 0x2000
	s_nop 0
	global_load_lds_dwordx4 v[200:201], off
	v_lshl_add_u64 v[200:201], s[24:25], 0, v[134:135]
	s_mov_b32 m0, s43
	s_nop 0
	global_load_lds_dwordx4 v[200:201], off
	s_mov_b32 m0, s44
	s_nop 0
	global_load_lds_dwordx4 v[224:225], off
	s_waitcnt vmcnt(8)
	s_waitcnt lgkmcnt(0)
	s_barrier
	s_setprio 1
	s_waitcnt lgkmcnt(0)
	v_mfma_f32_16x16x32_bf16 v[62:65], v[146:149], v[184:187], v[62:65]
	v_mfma_f32_16x16x32_bf16 v[54:57], v[154:157], v[184:187], v[54:57]
	v_mfma_f32_16x16x32_bf16 v[46:49], v[146:149], v[192:195], v[46:49]
	v_mfma_f32_16x16x32_bf16 v[38:41], v[154:157], v[192:195], v[38:41]
	v_mfma_f32_16x16x32_bf16 v[30:33], v[146:149], v[208:211], v[30:33]
	v_mfma_f32_16x16x32_bf16 v[22:25], v[154:157], v[208:211], v[22:25]
	v_mfma_f32_16x16x32_bf16 v[14:17], v[146:149], v[216:219], v[14:17]
	v_mfma_f32_16x16x32_bf16 v[6:9], v[154:157], v[216:219], v[6:9]
	v_mfma_f32_16x16x32_bf16 v[62:65], v[150:153], v[188:191], v[62:65]
	v_mfma_f32_16x16x32_bf16 v[54:57], v[158:161], v[188:191], v[54:57]
	v_mfma_f32_16x16x32_bf16 v[46:49], v[150:153], v[196:199], v[46:49]
	v_mfma_f32_16x16x32_bf16 v[38:41], v[158:161], v[196:199], v[38:41]
	v_mfma_f32_16x16x32_bf16 v[30:33], v[150:153], v[212:215], v[30:33]
	v_mfma_f32_16x16x32_bf16 v[22:25], v[158:161], v[212:215], v[22:25]
	v_mfma_f32_16x16x32_bf16 v[14:17], v[150:153], v[220:223], v[14:17]
	v_mfma_f32_16x16x32_bf16 v[6:9], v[158:161], v[220:223], v[6:9]
	s_setprio 0
	s_setprio 1
	v_mfma_f32_16x16x32_bf16 v[58:61], v[162:165], v[184:187], v[58:61]
	v_mfma_f32_16x16x32_bf16 v[50:53], v[176:179], v[184:187], v[50:53]
	v_mfma_f32_16x16x32_bf16 v[42:45], v[162:165], v[192:195], v[42:45]
	v_mfma_f32_16x16x32_bf16 v[34:37], v[176:179], v[192:195], v[34:37]
	v_mfma_f32_16x16x32_bf16 v[26:29], v[162:165], v[208:211], v[26:29]
	v_mfma_f32_16x16x32_bf16 v[18:21], v[176:179], v[208:211], v[18:21]
	v_mfma_f32_16x16x32_bf16 v[10:13], v[162:165], v[216:219], v[10:13]
	v_mfma_f32_16x16x32_bf16 v[2:5], v[176:179], v[216:219], v[2:5]
	v_mfma_f32_16x16x32_bf16 v[58:61], v[166:169], v[188:191], v[58:61]
	v_mfma_f32_16x16x32_bf16 v[50:53], v[180:183], v[188:191], v[50:53]
	v_mfma_f32_16x16x32_bf16 v[42:45], v[166:169], v[196:199], v[42:45]
	v_mfma_f32_16x16x32_bf16 v[34:37], v[180:183], v[196:199], v[34:37]
	v_mfma_f32_16x16x32_bf16 v[26:29], v[166:169], v[212:215], v[26:29]
	v_mfma_f32_16x16x32_bf16 v[18:21], v[180:183], v[212:215], v[18:21]
	v_mfma_f32_16x16x32_bf16 v[10:13], v[166:169], v[220:223], v[10:13]
	v_mfma_f32_16x16x32_bf16 v[2:5], v[180:183], v[220:223], v[2:5]
	s_setprio 0
	s_barrier
; #define PG8_STAGE(bufoff, gbase, voff) do { _Pragma("unroll") for (int _i = 0; _i < 2; ++_i) \
;         __builtin_amdgcn_global_load_lds((const unsigned*)((const char*)(gbase) + (voff)[_i]), (PG8_LAS unsigned*)(lds + (bufoff) + ldsw + _i * 8192), 16, 0, 0); } while (0)
; #define PG8_LDA(dst, b, h) do { _Pragma("unroll") for (int m = 0; m < 4; ++m) _Pragma("unroll") for (int k = 0; k < 2; ++k) dst[m][k] = *(const PG8_LAS bf16x8*)(lds + PG8_SA(b, h) + aoff + m * 2048 + k * 1024); } while (0)
; #define PG8_LDB(dst, b, h) do { _Pragma("unroll") for (int n = 0; n < 2; ++n) _Pragma("unroll") for (int k = 0; k < 2; ++k) dst[n][k] = *(const PG8_LAS bf16x8*)(lds + PG8_SB(b, h) + boff + n * 2048 + k * 1024); } while (0)
; #define PG8_MMA(ai, bj, At, Bt) do { __builtin_amdgcn_s_setprio(1); _Pragma("unroll") for (int m = 0; m < 4; ++m) _Pragma("unroll") for (int n = 0; n < 2; ++n) _Pragma("unroll") for (int k = 0; k < 2; ++k) \
;         acc[ai][bj][m][n] = __builtin_amdgcn_mfma_f32_16x16x32_bf16(Bt[n][k], At[m][k], acc[ai][bj][m][n], 0, 0, 0); __builtin_amdgcn_s_setprio(0); } while (0)
; #define PG8_WAIT_V(n) asm volatile("s_waitcnt vmcnt(" #n ")" ::: "memory")
; #define PG8_WAIT_L(n) asm volatile("s_waitcnt lgkmcnt(" #n ")" ::: "memory")
; #define PG8_BAR __builtin_amdgcn_s_barrier()
; #define PG8_SCHED __builtin_amdgcn_sched_barrier(0)
; template <class Epi, class Sched, bool ALIGN_EPI = false, bool SP2 = false>
; __device__ __forceinline__ void gemm_phase(PG8_LAS unsigned char* lds, const Gemm g, const Sched& S, const Epi& E, int wave_s) {
;     ...
;             PG8_LDB(B0, 1, 0); PG8_LDB(B1, 1, 1); PG8_SCHED; PG8_LDA(At, 1, 0); PG8_STAGE(PG8_SA(0, 1), a2 + hstepA, voffA);
;             PG8_WAIT_V(8); PG8_WAIT_L(0); PG8_BAR; PG8_MMA(0, 0, At, B0); PG8_MMA(0, 1, At, B1); PG8_BAR; PG8_SCHED;
	s_add_i32 s34, 0, 0x18000
	s_add_i32 s35, 0, 0x1c000
	v_add_u32_e32 v158, s34, v143
	v_add_u32_e32 v180, s35, v143
	ds_read_b128 v[146:149], v158
	ds_read_b128 v[150:153], v158 offset:1024
	ds_read_b128 v[154:157], v158 offset:2048
	ds_read_b128 v[158:161], v158 offset:3072
	ds_read_b128 v[162:165], v180
	ds_read_b128 v[166:169], v180 offset:1024
	ds_read_b128 v[176:179], v180 offset:2048
	ds_read_b128 v[180:183], v180 offset:3072
	s_add_u32 s24, s24, 0x80000
	s_addc_u32 s25, s25, 0
	s_mov_b32 m0, s45
	v_lshl_add_u64 v[226:227], s[24:25], 0, v[134:135]
	ds_read_b128 v[184:187], v145 offset:32768
	ds_read_b128 v[188:191], v145 offset:33792
	ds_read_b128 v[192:195], v145 offset:34816
	ds_read_b128 v[196:199], v145 offset:35840
	ds_read_b128 v[208:211], v145 offset:36864
	ds_read_b128 v[212:215], v145 offset:37888
	ds_read_b128 v[216:219], v145 offset:38912
	ds_read_b128 v[220:223], v145 offset:39936
	global_load_lds_dwordx4 v[226:227], off
	v_lshl_add_u64 v[226:227], s[24:25], 0, v[132:133]
	s_mov_b32 m0, s46
	s_nop 0
	global_load_lds_dwordx4 v[226:227], off
	s_waitcnt vmcnt(8)
	s_waitcnt lgkmcnt(0)
	s_barrier
	s_setprio 1
	s_waitcnt lgkmcnt(0)
	v_mfma_f32_16x16x32_bf16 v[126:129], v[146:149], v[184:187], v[126:129]
	v_mfma_f32_16x16x32_bf16 v[118:121], v[154:157], v[184:187], v[118:121]
	v_mfma_f32_16x16x32_bf16 v[110:113], v[146:149], v[192:195], v[110:113]
	v_mfma_f32_16x16x32_bf16 v[102:105], v[154:157], v[192:195], v[102:105]
	v_mfma_f32_16x16x32_bf16 v[94:97], v[146:149], v[208:211], v[94:97]
	v_mfma_f32_16x16x32_bf16 v[86:89], v[154:157], v[208:211], v[86:89]
	v_mfma_f32_16x16x32_bf16 v[78:81], v[146:149], v[216:219], v[78:81]
	v_mfma_f32_16x16x32_bf16 v[70:73], v[154:157], v[216:219], v[70:73]
	v_mfma_f32_16x16x32_bf16 v[126:129], v[150:153], v[188:191], v[126:129]
	v_mfma_f32_16x16x32_bf16 v[118:121], v[158:161], v[188:191], v[118:121]
	v_mfma_f32_16x16x32_bf16 v[110:113], v[150:153], v[196:199], v[110:113]
	v_mfma_f32_16x16x32_bf16 v[102:105], v[158:161], v[196:199], v[102:105]
	v_mfma_f32_16x16x32_bf16 v[94:97], v[150:153], v[212:215], v[94:97]
	v_mfma_f32_16x16x32_bf16 v[86:89], v[158:161], v[212:215], v[86:89]
	v_mfma_f32_16x16x32_bf16 v[78:81], v[150:153], v[220:223], v[78:81]
	v_mfma_f32_16x16x32_bf16 v[70:73], v[158:161], v[220:223], v[70:73]
	s_setprio 0
	s_setprio 1
	v_mfma_f32_16x16x32_bf16 v[122:125], v[162:165], v[184:187], v[122:125]
	v_mfma_f32_16x16x32_bf16 v[114:117], v[176:179], v[184:187], v[114:117]
	v_mfma_f32_16x16x32_bf16 v[106:109], v[162:165], v[192:195], v[106:109]
	v_mfma_f32_16x16x32_bf16 v[98:101], v[176:179], v[192:195], v[98:101]
	v_mfma_f32_16x16x32_bf16 v[90:93], v[162:165], v[208:211], v[90:93]
	v_mfma_f32_16x16x32_bf16 v[82:85], v[176:179], v[208:211], v[82:85]
	v_mfma_f32_16x16x32_bf16 v[74:77], v[162:165], v[216:219], v[74:77]
	v_mfma_f32_16x16x32_bf16 v[66:69], v[176:179], v[216:219], v[66:69]
	v_mfma_f32_16x16x32_bf16 v[122:125], v[166:169], v[188:191], v[122:125]
	v_mfma_f32_16x16x32_bf16 v[114:117], v[180:183], v[188:191], v[114:117]
	v_mfma_f32_16x16x32_bf16 v[106:109], v[166:169], v[196:199], v[106:109]
	v_mfma_f32_16x16x32_bf16 v[98:101], v[180:183], v[196:199], v[98:101]
	v_mfma_f32_16x16x32_bf16 v[90:93], v[166:169], v[212:215], v[90:93]
	v_mfma_f32_16x16x32_bf16 v[82:85], v[180:183], v[212:215], v[82:85]
	v_mfma_f32_16x16x32_bf16 v[74:77], v[166:169], v[220:223], v[74:77]
	v_mfma_f32_16x16x32_bf16 v[66:69], v[180:183], v[220:223], v[66:69]
	s_setprio 0
	s_barrier
; #define PG8_STAGE(bufoff, gbase, voff) do { _Pragma("unroll") for (int _i = 0; _i < 2; ++_i) \
;         __builtin_amdgcn_global_load_lds((const unsigned*)((const char*)(gbase) + (voff)[_i]), (PG8_LAS unsigned*)(lds + (bufoff) + ldsw + _i * 8192), 16, 0, 0); } while (0)
; #define PG8_LDA(dst, b, h) do { _Pragma("unroll") for (int m = 0; m < 4; ++m) _Pragma("unroll") for (int k = 0; k < 2; ++k) dst[m][k] = *(const PG8_LAS bf16x8*)(lds + PG8_SA(b, h) + aoff + m * 2048 + k * 1024); } while (0)
; #define PG8_WAIT_V(n) asm volatile("s_waitcnt vmcnt(" #n ")" ::: "memory")
; #define PG8_BAR __builtin_amdgcn_s_barrier()
; template <class Epi, class Sched, bool ALIGN_EPI = false, bool SP2 = false>
; __device__ __forceinline__ void gemm_phase(PG8_LAS unsigned char* lds, const Gemm g, const Sched& S, const Epi& E, int wave_s) {
;     ...
;         for (int t = 0; t < nt; t += 2) {
;             const bool last = (t == nt - 2);
;             const char* a1 = cA + (size_t)(t + 1) * kstep;
;             const char* a2 = last ? nA : cA + (size_t)(t + 2) * kstep; const char* b2 = last ? nB : cB + (size_t)(t + 2) * kstep;
;             const char* a3 = a2 + kstep; const char* b3 = b2 + kstep;
;             if (last && has_next) S.a_ready(nxt);
;             if constexpr (Epi::HAS_MID) { if (t == nt / 2) E.mid(acc, cur, wr, wc, fr, fq); }
;             if constexpr (SP2) {
;             PG8_LDB(B0, 0, 0); PG8_LDB(B1, 0, 1); PG8_SCHED; PG8_LDA(At, 0, 0); PG8_STAGE(PG8_SA(1, 1), a1 + hstepA, voffA);
;             PG8_WAIT_V(8); PG8_WAIT_L(0); PG8_BAR; PG8_MMA(0, 0, At, B0); PG8_MMA(0, 1, At, B1); PG8_BAR; PG8_SCHED;
;             PG8_LDA(At, 0, 1); PG8_STAGE(PG8_SB(0, 0), b2, voffB); PG8_STAGE(PG8_SB(0, 1), b2 + hstepB, voffB); PG8_STAGE(PG8_SA(0, 0), a2, voffA);
;             PG8_WAIT_V(8); PG8_WAIT_L(0); PG8_BAR; PG8_MMA(1, 0, At, B0); PG8_MMA(1, 1, At, B1); PG8_BAR; PG8_SCHED;
;             PG8_LDB(B0, 1, 0); PG8_LDB(B1, 1, 1); PG8_SCHED; PG8_LDA(At, 1, 0); PG8_STAGE(PG8_SA(0, 1), a2 + hstepA, voffA);
;             PG8_WAIT_V(8); PG8_WAIT_L(0); PG8_BAR; PG8_MMA(0, 0, At, B0); PG8_MMA(0, 1, At, B1); PG8_BAR; PG8_SCHED;
;             PG8_LDA(At, 1, 1); PG8_STAGE(PG8_SB(1, 0), b3, voffB); PG8_STAGE(PG8_SB(1, 1), b3 + hstepB, voffB); PG8_STAGE(PG8_SA(1, 0), a3, voffA);
;             PG8_WAIT_V(8); PG8_WAIT_L(0); PG8_BAR; PG8_MMA(1, 0, At, B0); PG8_MMA(1, 1, At, B1); PG8_BAR; PG8_SCHED;
	s_add_i32 s24, s34, s42
	s_mov_b64 s[100:101], 0x8000
	v_lshl_add_u64 v[140:141], v[140:141], 0, s[100:101]
	s_mov_b32 m0, s24
	ds_read_b128 v[184:187], v145 offset:49152
	ds_read_b128 v[188:191], v145 offset:50176
	ds_read_b128 v[192:195], v145 offset:51200
	ds_read_b128 v[196:199], v145 offset:52224
	ds_read_b128 v[208:211], v145 offset:53248
	ds_read_b128 v[212:215], v145 offset:54272
	ds_read_b128 v[216:219], v145 offset:55296
	ds_read_b128 v[220:223], v145 offset:56320
	global_load_lds_dwordx4 v[140:141], off
	s_add_i32 m0, s24, 0x2000
	s_add_u32 s20, s20, 0xc000
	v_lshl_add_u64 v[140:141], v[170:171], 0, s[100:101]
	s_addc_u32 s21, s21, 0
	s_add_i32 s24, s35, s42
	global_load_lds_dwordx4 v[140:141], off
	v_lshl_add_u64 v[140:141], s[20:21], 0, v[0:1]
	s_mov_b32 m0, s24
	s_nop 0
	global_load_lds_dwordx4 v[140:141], off
	v_lshl_add_u64 v[140:141], s[20:21], 0, v[130:131]
	s_add_i32 m0, s24, 0x2000
	s_nop 0
	global_load_lds_dwordx4 v[140:141], off
	v_lshl_add_u64 v[140:141], v[200:201], 0, s[30:31]
	s_mov_b32 m0, s47
	s_nop 0
	global_load_lds_dwordx4 v[140:141], off
	v_lshl_add_u64 v[140:141], v[224:225], 0, s[30:31]
	s_mov_b32 m0, s48
	s_nop 0
	global_load_lds_dwordx4 v[140:141], off
	s_waitcnt vmcnt(8)
	s_waitcnt lgkmcnt(0)
	s_barrier
	s_setprio 1
	s_waitcnt lgkmcnt(0)
	v_mfma_f32_16x16x32_bf16 v[62:65], v[146:149], v[184:187], v[62:65]
	v_mfma_f32_16x16x32_bf16 v[54:57], v[154:157], v[184:187], v[54:57]
	v_mfma_f32_16x16x32_bf16 v[46:49], v[146:149], v[192:195], v[46:49]
	v_mfma_f32_16x16x32_bf16 v[38:41], v[154:157], v[192:195], v[38:41]
	v_mfma_f32_16x16x32_bf16 v[30:33], v[146:149], v[208:211], v[30:33]
	v_mfma_f32_16x16x32_bf16 v[22:25], v[154:157], v[208:211], v[22:25]
	v_mfma_f32_16x16x32_bf16 v[14:17], v[146:149], v[216:219], v[14:17]
	v_mfma_f32_16x16x32_bf16 v[6:9], v[154:157], v[216:219], v[6:9]
	v_mfma_f32_16x16x32_bf16 v[62:65], v[150:153], v[188:191], v[62:65]
	v_mfma_f32_16x16x32_bf16 v[54:57], v[158:161], v[188:191], v[54:57]
	v_mfma_f32_16x16x32_bf16 v[46:49], v[150:153], v[196:199], v[46:49]
	v_mfma_f32_16x16x32_bf16 v[38:41], v[158:161], v[196:199], v[38:41]
	v_mfma_f32_16x16x32_bf16 v[30:33], v[150:153], v[212:215], v[30:33]
	v_mfma_f32_16x16x32_bf16 v[22:25], v[158:161], v[212:215], v[22:25]
	v_mfma_f32_16x16x32_bf16 v[14:17], v[150:153], v[220:223], v[14:17]
	v_mfma_f32_16x16x32_bf16 v[6:9], v[158:161], v[220:223], v[6:9]
	s_setprio 0
	s_setprio 1
	v_mfma_f32_16x16x32_bf16 v[58:61], v[162:165], v[184:187], v[58:61]
	v_mfma_f32_16x16x32_bf16 v[50:53], v[176:179], v[184:187], v[50:53]
	v_mfma_f32_16x16x32_bf16 v[42:45], v[162:165], v[192:195], v[42:45]
	v_mfma_f32_16x16x32_bf16 v[34:37], v[176:179], v[192:195], v[34:37]
	v_mfma_f32_16x16x32_bf16 v[26:29], v[162:165], v[208:211], v[26:29]
	v_mfma_f32_16x16x32_bf16 v[18:21], v[176:179], v[208:211], v[18:21]
	v_mfma_f32_16x16x32_bf16 v[10:13], v[162:165], v[216:219], v[10:13]
	v_mfma_f32_16x16x32_bf16 v[2:5], v[176:179], v[216:219], v[2:5]
	v_mfma_f32_16x16x32_bf16 v[58:61], v[166:169], v[188:191], v[58:61]
	v_mfma_f32_16x16x32_bf16 v[50:53], v[180:183], v[188:191], v[50:53]
	v_mfma_f32_16x16x32_bf16 v[42:45], v[166:169], v[196:199], v[42:45]
	v_mfma_f32_16x16x32_bf16 v[34:37], v[180:183], v[196:199], v[34:37]
	v_mfma_f32_16x16x32_bf16 v[26:29], v[166:169], v[212:215], v[26:29]
	v_mfma_f32_16x16x32_bf16 v[18:21], v[180:183], v[212:215], v[18:21]
	v_mfma_f32_16x16x32_bf16 v[10:13], v[166:169], v[220:223], v[10:13]
	v_mfma_f32_16x16x32_bf16 v[2:5], v[180:183], v[220:223], v[2:5]
	s_setprio 0
	s_barrier
	s_add_i32 s55, s55, 2
	s_add_u32 s51, s51, 0x10000
	s_addc_u32 s54, s54, 0
	s_add_u32 s18, s18, 0x100
	s_addc_u32 s19, s19, 0
	s_cmp_gt_u32 s55, 29
	s_cbranch_scc0 .LBB0_1797
	s_and_b64 vcc, exec, s[8:9]
	s_cbranch_vccz .LBB0_1800
	s_barrier
